# hand-written shared GEMM 256x128 tile LDS-DMA ring, 4 sites, bf16 MFMA same as baseline
# speedup vs baseline: 1.0408x; 1.0408x over previous
; #define LAS __attribute__((address_space(3)))
; __global__ void __launch_bounds__(THREADS, 2) fwd_megakernel(Params p) {
;   __shared__ __attribute__((aligned(16))) char smem[79872];
;   cg::grid_group grid = cg::this_grid();
;   volatile LAS unsigned* xst = (volatile LAS unsigned*)(smem + 79856);
;   if (threadIdx.x == 0) { xst[0] = 0u; xst[1] = 0u; }
;   __syncthreads();
_Z14fwd_megakernel6Params:
	v_writelane_b32 v255, s2, 0
	v_writelane_b32 v255, s0, 1
	v_writelane_b32 v255, s1, 2
	s_load_dwordx8 s[20:27], s[0:1], 0xe0
	s_load_dwordx8 s[4:11], s[0:1], 0xc0
	s_load_dword s78, s[0:1], 0x100
	s_add_u32 s12, s0, 0xf8
	s_addc_u32 s13, s1, 0
	v_and_b32_e32 v143, 0x3ff, v0
	v_writelane_b32 v236, s12, 0
	v_cmp_ne_u32_e64 s[28:29], 0, v143
	s_nop 0
	v_writelane_b32 v236, s13, 1
	v_cmp_eq_u32_e64 s[12:13], 0, v143
	s_mov_b64 s[14:15], exec
	s_nop 0
	v_writelane_b32 v236, s12, 2
	s_nop 1
	v_writelane_b32 v236, s13, 3
	s_and_b64 s[12:13], s[14:15], s[12:13]
	s_mov_b64 exec, s[12:13]
	s_cbranch_execz .LBB0_2
	v_mov_b32_e32 v1, 0
	v_mov_b32_e32 v2, 0x137f0
	ds_write_b32 v2, v1
	v_mov_b32_e32 v2, 0x137f4
	ds_write_b32 v2, v1

; __global__ void __launch_bounds__(THREADS, 2) fwd_megakernel(Params p) {
;     ...
;   for (int layer = 0; layer < 2; ++layer) {
;     const bf16_t* wl = (const bf16_t*)(p.ws + OFF_W) + (size_t)layer * WL;
;     const int MT_ALL = NTOK / 128, MT_LAT = NLAT / 128;
;     const int MT_RES = (layer == 0) ? MT_ALL : MT_LAT;
;     phase_norm(p, layer, 0, NTOK);
;     xcd_barrier(xb);
;     gemm_phase<EPI_U>(p, layer, (const bf16_t*)(p.ws + OFF_H), D, wl + W_IN, D, D, MT_ALL, INP / 128, smem);
.LBB0_382:
	s_or_b64 exec, exec, s[0:1]
	v_writelane_b32 v255, s52, 3
	s_mul_i32 s0, s52, 0xb60000
	s_mov_b32 s1, s92
	s_lshl_b64 s[0:1], s[0:1], 1
	v_readlane_b32 s6, v236, 40
	s_add_u32 s6, s6, s0
	v_readlane_b32 s0, v236, 41
	s_addc_u32 s7, s0, s1
	v_readlane_b32 s0, v235, 32
	v_readlane_b32 s1, v235, 33
	v_writelane_b32 v234, s6, 52
	s_waitcnt lgkmcnt(0)
	v_mov_b32_e32 v0, v143
	s_andn2_b64 vcc, exec, s[0:1]
	v_writelane_b32 v234, s7, 53
	s_barrier
	s_cbranch_vccnz .LBB0_458
	s_mov_b32 s100, 0
	s_branch .Lmg_entry

; __global__ void __launch_bounds__(THREADS, 2) fwd_megakernel(Params p) {
;     ...
;     gemm_phase<EPI_RES1>(p, layer, (const bf16_t*)(p.ws + OFF_U), D, wl + W_OUT, D, D, MT_RES, D / 128, smem);
.LBB0_1540:
	s_or_b64 exec, exec, s[0:1]
	v_cvt_f32_u32_e32 v1, s46
	s_lshl_b32 s47, s46, 3
	s_cmp_lt_i32 s51, s47
	s_waitcnt lgkmcnt(0)
	v_mov_b32_e32 v0, v143
	v_rcp_iflag_f32_e32 v212, v1
	s_cselect_b64 s[6:7], -1, 0
	s_cmp_ge_i32 s51, s47
	s_barrier
	s_cbranch_scc1 .LBB0_1546
	s_mov_b32 s100, 1
	s_branch .Lmg_entry

; __global__ void __launch_bounds__(THREADS, 2) fwd_megakernel(Params p) {
;     ...
;     gemm_phase<EPI_SWIGLU>(p, layer, (const bf16_t*)(p.ws + OFF_H), D, wl + W_13, D, D, MT_RES, 2 * FFH / 128, smem);
.LBB0_1645:
	s_or_b64 exec, exec, s[0:1]
	s_mul_i32 s10, s46, 44
	s_waitcnt lgkmcnt(0)
	v_mov_b32_e32 v0, v143
	s_cmp_ge_i32 s51, s10
	s_barrier
	s_cbranch_scc1 .LBB0_1650
	s_mov_b32 s100, 2
	s_branch .Lmg_entry

; __global__ void __launch_bounds__(THREADS, 2) fwd_megakernel(Params p) {
;     ...
;     gemm_phase<EPI_RES2>(p, layer, (const bf16_t*)(p.ws + OFF_U), FFH, wl + W_2, FFH, FFH, MT_RES, D / 128, smem);
.LBB0_1698:
	s_or_b64 exec, exec, s[0:1]
	s_waitcnt lgkmcnt(0)
	v_mov_b32_e32 v0, v143
	s_andn2_b64 vcc, exec, s[6:7]
	s_barrier
	s_cbranch_vccnz .LBB0_1711
	s_mov_b32 s100, 3
	s_branch .Lmg_entry

; DI int get_tid() { int t = threadIdx.x; asm volatile("" : "+v"(t)); return t; }
; template <int EPI>
; DI void gemm_phase(const Params& p, int layer, const bf16_t* __restrict__ A, int lda, const bf16_t* __restrict__ Bt, int ldb, int K, int MT, int NT,
;                    char* smem, bool rev = false) {
;   bf16_t* sA = (bf16_t*)smem;
;   bf16_t* sB = sA + 2 * 128 * LDT;
;   const int tid = get_tid(), lane = tid & 63, wave = tid >> 6, wr = wave >> 1, wc = wave & 1;
;   const int total = MT * NT;
;   int t = rev ? (int)(gridDim.x - 1 - blockIdx.x) : (int)blockIdx.x;
;   if (t >= total) return;
;   uint4 pa0, pa1, pa2, pa3, pb0, pb1, pb2, pb3, qa0, qa1, qa2, qa3, qb0, qb1, qb2, qb3;
;   const int lr = tid >> 3, lc = (tid & 7) * 8;
;   const int nk = K >> 6;
;   const int soff = lr * LDT + lc;
;   const int aoff = (wr * 64 + (lane & 31)) * LDT + (lane >> 5) * 8;
;   const int boff = (wc * 64 + (lane & 31)) * LDT + (lane >> 5) * 8;
;   int mt, nt; tile_map(t, MT, NT, mt, nt);
;   int m0 = mt * 128, n0 = nt * 128;
;   const bf16_t* Agl = A + (size_t)(m0 + lr) * lda + lc;
;   const bf16_t* Bgl = Bt + (size_t)(n0 + lr) * ldb + lc;
; __global__ void __launch_bounds__(THREADS, 2) fwd_megakernel(Params p) {
;     ...
;     gemm_phase<EPI_U>(p, layer, (const bf16_t*)(p.ws + OFF_H), D, wl + W_IN, D, D, MT_ALL, INP / 128, smem);
;     xcd_barrier(xb);
;     phase_prep(p, layer, smem);
;     xcd_barrier(xb);
;     phase_mix_a(p, layer, smem);
;     xcd_barrier(xb);
;     phase_attn(p, layer, smem);
;     xcd_barrier(xb);
;     gemm_phase<EPI_RES1>(p, layer, (const bf16_t*)(p.ws + OFF_U), D, wl + W_OUT, D, D, MT_RES, D / 128, smem);
;     xcd_barrier(xb);
;     phase_norm(p, layer, 1, MT_RES * 128);
;     xcd_barrier(xb);
;     gemm_phase<EPI_SWIGLU>(p, layer, (const bf16_t*)(p.ws + OFF_H), D, wl + W_13, D, D, MT_RES, 2 * FFH / 128, smem);
;     xcd_barrier(xb);
;     gemm_phase<EPI_RES2>(p, layer, (const bf16_t*)(p.ws + OFF_U), FFH, wl + W_2, FFH, FFH, MT_RES, D / 128, smem);
.Lmg_entry:
	v_writelane_b32 v254, s52, 0
	v_writelane_b32 v254, s53, 1
	v_writelane_b32 v254, s54, 2
	v_writelane_b32 v254, s55, 3
	v_writelane_b32 v254, s56, 4
	v_writelane_b32 v254, s57, 5
	v_writelane_b32 v254, s58, 6
	v_writelane_b32 v254, s59, 7
	v_writelane_b32 v254, s60, 8
	v_writelane_b32 v254, s61, 9
	v_writelane_b32 v254, s62, 10
	v_writelane_b32 v254, s63, 11
	v_writelane_b32 v254, s64, 12
	v_writelane_b32 v254, s65, 13
	v_writelane_b32 v254, s66, 14
	v_writelane_b32 v254, s67, 15
	v_writelane_b32 v254, s68, 16
	v_writelane_b32 v254, s69, 17
	v_writelane_b32 v254, s70, 18
	v_writelane_b32 v254, s71, 19
	v_writelane_b32 v254, s72, 20
	v_writelane_b32 v254, s73, 21
	v_writelane_b32 v254, s74, 22
	v_writelane_b32 v254, s75, 23
	v_writelane_b32 v254, s76, 24
	v_writelane_b32 v254, s77, 25
	v_writelane_b32 v254, s78, 26
	v_writelane_b32 v254, s79, 27
	v_writelane_b32 v254, s80, 28
	v_writelane_b32 v254, s81, 29
	v_writelane_b32 v254, s82, 30
	v_writelane_b32 v254, s83, 31
	v_writelane_b32 v254, s84, 32
	v_writelane_b32 v254, s85, 33
	v_writelane_b32 v254, s86, 34
	v_writelane_b32 v254, s87, 35
	v_writelane_b32 v254, s88, 36
	v_writelane_b32 v254, s89, 37
	v_writelane_b32 v254, s90, 38
	v_writelane_b32 v254, s91, 39
	s_mov_b32 s52, s100
	v_readlane_b32 s53, v255, 3
	s_nop 3
	v_and_b32_e32 v140, 63, v143
	v_lshrrev_b32_e32 v184, 6, v143
	v_and_b32_e32 v227, 31, v143
	v_bfe_u32 v228, v143, 5, 1
	v_readfirstlane_b32 s77, v184
	s_nop 3
	s_lshr_b32 s78, s77, 1
	s_and_b32 s79, s77, 1
	s_mul_i32 s80, s77, 0x1800
	v_readlane_b32 s66, v255, 0
	s_mov_b32 s65, s26
	s_mul_i32 s0, s53, 0x16c0000
	s_add_u32 s0, s0, 0x1a580000
	s_add_u32 s56, s24, s0
	s_addc_u32 s57, s25, 0
	s_mov_b32 s61, 17
	s_mov_b32 s63, 3856
	s_cmp_eq_u32 s52, 0
	s_cbranch_scc1 .Lmg_mt_1
	s_cmp_eq_u32 s53, 0
	s_cbranch_scc1 .Lmg_mt_1
	s_mov_b32 s61, 16
	s_mov_b32 s63, 4096
.Lmg_mt_1:
	s_cmp_eq_u32 s52, 1
	s_cbranch_scc1 .Lmg_par_3
	s_cmp_eq_u32 s52, 2
	s_cbranch_scc1 .Lmg_par_4
	s_cmp_eq_u32 s52, 3
	s_cbranch_scc1 .Lmg_par_5
.Lmg_par_2:
	s_add_u32 s54, s24, 0x15980000
	s_addc_u32 s55, s25, 0
	s_movk_i32 s58, 0x800
	s_movk_i32 s59, 0x800
	s_movk_i32 s60, 32
	s_movk_i32 s62, 15
	s_movk_i32 s69, 9363
	s_branch .Lmg_pare_6
.Lmg_par_3:
	s_mov_b32 s54, s24
	s_mov_b32 s55, s25
	s_movk_i32 s58, 0x800
	s_movk_i32 s59, 0x800
	s_movk_i32 s60, 32
	s_movk_i32 s62, 8
	s_movk_i32 s69, 8192
	s_add_u32 s56, s56, 0x3c0000
	s_addc_u32 s57, s57, 0
	s_branch .Lmg_pare_6
.Lmg_par_4:
	s_add_u32 s54, s24, 0x15980000
	s_addc_u32 s55, s25, 0
	s_movk_i32 s58, 0x800
	s_movk_i32 s59, 0x800
	s_movk_i32 s60, 32
	s_movk_i32 s62, 44
	s_movk_i32 s69, 16384
	s_add_u32 s56, s56, 0x5c0000
	s_addc_u32 s57, s57, 0
	s_branch .Lmg_pare_6
.Lmg_par_5:
	s_mov_b32 s54, s24
	s_mov_b32 s55, s25
	s_movk_i32 s58, 0x1600
	s_movk_i32 s59, 0x1600
	s_movk_i32 s60, 88
	s_movk_i32 s62, 8
	s_movk_i32 s69, 8192
	s_add_u32 s56, s56, 0x10c0000
	s_addc_u32 s57, s57, 0
.Lmg_pare_6:
	s_lshl_b32 s0, s61, 3
	s_mul_i32 s64, s0, s62
	v_lshrrev_b32_e32 v184, 2, v140
	v_and_b32_e32 v185, 3, v140
	v_bfe_u32 v186, v140, 4, 2
	v_xor_b32_e32 v185, v185, v186
	v_lshlrev_b32_e32 v185, 4, v185
	s_lshl_b32 s0, s77, 6
	v_add_u32_e32 v186, s0, v184
	v_mul_lo_u32 v186, v186, s58
	v_add_u32_e32 v213, v186, v185
	s_lshl_b32 s0, s58, 4
	s_sub_u32 s0, s0, 0x400
	v_add_u32_e32 v214, s0, v213
	v_add_u32_e32 v215, s0, v214
	v_add_u32_e32 v216, s0, v215
	s_lshl_b32 s0, s77, 5
	v_add_u32_e32 v186, s0, v184
	v_mul_lo_u32 v186, v186, s59
	v_add_u32_e32 v217, v186, v185
	s_lshl_b32 s0, s59, 4
	s_sub_u32 s0, s0, 0x400
	v_add_u32_e32 v218, s0, v217
	v_bfe_u32 v184, v140, 2, 2
	v_xor_b32_e32 v185, v184, v228
	v_xor_b32_e32 v186, 2, v185
	v_lshlrev_b32_e32 v187, 6, v227
	v_lshl_add_u32 v185, v185, 4, v187
	v_lshl_add_u32 v186, v186, 4, v187
	s_mul_i32 s0, s78, 0x3000
	v_add_u32_e32 v219, s0, v185
	v_add_u32_e32 v220, s0, v186
	s_mul_i32 s0, s79, 0x3000
	s_add_u32 s0, s0, 0x1000
	v_add_u32_e32 v221, s0, v185
	v_add_u32_e32 v222, s0, v186
.Lmg_tile:
	s_cmp_ge_u32 s66, s64
	s_cbranch_scc1 .Lmg_done
	s_and_b32 s0, s66, 7
	s_lshr_b32 s1, s66, 3
	s_lshr_b32 s10, s1, 3
	s_mul_i32 s10, s10, s63
	s_lshr_b32 s10, s10, 16
	s_lshr_b32 s11, s62, 3
	s_mov_b32 s12, 8
	s_mov_b32 s13, 0x2000
	s_cmp_ge_u32 s10, s11
	s_cbranch_scc0 .Lmg_tm_7
	s_mov_b32 s10, s11
	s_and_b32 s12, s62, 7
	s_mov_b32 s13, s69
; DI void tile_map(int t, int MT, int NT, int& mt, int& nt) {
;   const int xc = t & 7, j = t >> 3, mtx = MT >> 3, full = NT >> 3, per = mtx * 8;
;   int sc = j / per, rem, w;
;   if (sc < full) { rem = j - sc * per; w = 8; }
;   else { sc = full; rem = j - full * per; w = NT & 7; }
;   const int m = rem / w, nn = rem - m * w;
;   mt = xc * mtx + m; nt = sc * 8 + nn;
; }
; template <int EPI>
; DI void gemm_phase(const Params& p, int layer, const bf16_t* __restrict__ A, int lda, const bf16_t* __restrict__ Bt, int ldb, int K, int MT, int NT,
;                    char* smem, bool rev = false) {
;     ...
;   G_LOAD(p, 0)
;   G_LOAD(q, 64)
;   for (;;) {
;     G_WRITE(p, 0)
;     __syncthreads();
;     if (nk > 2) G_LOAD(p, 128)
;     f32x16 acc[2][2];
; #pragma unroll
;     for (int i = 0; i < 2; ++i)
; #pragma unroll
;       for (int j = 0; j < 2; ++j)
; #pragma unroll
;         for (int r = 0; r < 16; ++r) acc[i][j][r] = 0.f;
;     for (int kt = 0; kt < nk; kt += 2) {
;       G_COMPUTE(0)
;       G_WRITE(q, 1)
;       __syncthreads();
;       if (kt + 3 < nk) G_LOAD(q, (kt + 3) << 6)
;       G_COMPUTE(1)
.Lmg_tm_7:
	s_lshl_b32 s28, s61, 3
	s_mul_i32 s28, s28, s10
	s_sub_u32 s28, s1, s28
	s_mul_i32 s29, s28, s13
	s_lshr_b32 s29, s29, 16
	s_mul_i32 s44, s29, s12
	s_sub_u32 s44, s28, s44
	s_mul_i32 s0, s0, s61
	s_add_u32 s0, s0, s29
	s_lshl_b32 s10, s10, 3
	s_add_u32 s10, s10, s44
	s_lshl_b32 s67, s0, 8
	s_lshl_b32 s68, s10, 7
	s_mul_i32 s0, s67, s58
	s_add_u32 s70, s54, s0
	s_addc_u32 s71, s55, 0
	s_mul_i32 s0, s68, s59
	s_add_u32 s72, s56, s0
	s_addc_u32 s73, s57, 0
	s_barrier
	s_mov_b32 s74, s80
	s_mov_b32 m0, s74
	s_nop 0
	global_load_lds_dwordx4 v213, s[70:71] offset:0
	global_load_lds_dwordx4 v214, s[70:71] offset:1024
	global_load_lds_dwordx4 v215, s[70:71] offset:2048
	global_load_lds_dwordx4 v216, s[70:71] offset:3072
	s_add_u32 m0, s74, 0x1000
	s_nop 0
	global_load_lds_dwordx4 v217, s[72:73] offset:0
	global_load_lds_dwordx4 v218, s[72:73] offset:1024
	s_add_u32 s70, s70, 64
	s_addc_u32 s71, s71, 0
	s_add_u32 s72, s72, 64
	s_addc_u32 s73, s73, 0
	s_add_u32 s74, s80, 0x6000
	s_mov_b32 m0, s74
	s_nop 0
	global_load_lds_dwordx4 v213, s[70:71] offset:0
	global_load_lds_dwordx4 v214, s[70:71] offset:1024
	global_load_lds_dwordx4 v215, s[70:71] offset:2048
	global_load_lds_dwordx4 v216, s[70:71] offset:3072
	s_add_u32 m0, s74, 0x1000
	s_nop 0
	global_load_lds_dwordx4 v217, s[72:73] offset:0
	global_load_lds_dwordx4 v218, s[72:73] offset:1024
	s_add_u32 s70, s70, 64
	s_addc_u32 s71, s71, 0
	s_add_u32 s72, s72, 64
	s_addc_u32 s73, s73, 0
	s_add_u32 s74, s80, 0xc000
	s_mov_b32 s75, 0
	v_mov_b32_e32 v223, v219
	v_mov_b32_e32 v225, v221
	v_mov_b32_e32 v224, v220
	v_mov_b32_e32 v226, v222
	s_sub_u32 s76, s60, 3
	s_waitcnt vmcnt(6)
	s_barrier
	ds_read_b128 v[128:131], v225
	ds_read_b128 v[132:135], v225 offset:6144
	ds_read_b128 v[144:147], v223
	ds_read_b128 v[148:151], v223 offset:2048
	ds_read_b128 v[152:155], v223 offset:6144
	ds_read_b128 v[156:159], v223 offset:8192
	ds_read_b128 v[160:163], v226
	ds_read_b128 v[164:167], v226 offset:6144
	ds_read_b128 v[168:171], v224
	ds_read_b128 v[172:175], v224 offset:2048
	ds_read_b128 v[176:179], v224 offset:6144
	ds_read_b128 v[180:183], v224 offset:8192
	s_mov_b32 m0, s74
	s_nop 0
	global_load_lds_dwordx4 v213, s[70:71] offset:0
	global_load_lds_dwordx4 v214, s[70:71] offset:1024
	global_load_lds_dwordx4 v215, s[70:71] offset:2048
	global_load_lds_dwordx4 v216, s[70:71] offset:3072
	s_add_u32 m0, s74, 0x1000
	s_nop 0
	global_load_lds_dwordx4 v217, s[72:73] offset:0
	global_load_lds_dwordx4 v218, s[72:73] offset:1024
	s_add_u32 s70, s70, 64
	s_addc_u32 s71, s71, 0
	s_add_u32 s72, s72, 64
	s_addc_u32 s73, s73, 0
	s_add_u32 s74, s74, 0x6000
	s_sub_u32 s1, s74, 0x12000
	s_add_u32 s0, s80, 0x12000
	s_cmp_ge_u32 s74, s0
	s_cselect_b32 s74, s1, s74
	s_add_u32 s75, s75, 0x6000
	s_cmp_eq_u32 s75, 0x12000
	s_cselect_b32 s75, 0, s75
	s_waitcnt lgkmcnt(9)
	v_mfma_f32_32x32x16_bf16 v[0:15], v[144:147], v[128:131], 0
	v_mfma_f32_32x32x16_bf16 v[16:31], v[144:147], v[132:135], 0
	s_waitcnt lgkmcnt(8)
	v_mfma_f32_32x32x16_bf16 v[32:47], v[148:151], v[128:131], 0
	v_mfma_f32_32x32x16_bf16 v[48:63], v[148:151], v[132:135], 0
	s_waitcnt lgkmcnt(7)
	v_mfma_f32_32x32x16_bf16 v[64:79], v[152:155], v[128:131], 0
	v_mfma_f32_32x32x16_bf16 v[80:95], v[152:155], v[132:135], 0
	s_waitcnt lgkmcnt(6)
	v_mfma_f32_32x32x16_bf16 v[96:111], v[156:159], v[128:131], 0
	v_mfma_f32_32x32x16_bf16 v[112:127], v[156:159], v[132:135], 0
	s_waitcnt lgkmcnt(3)
	v_mfma_f32_32x32x16_bf16 v[0:15], v[168:171], v[160:163], v[0:15]
	v_mfma_f32_32x32x16_bf16 v[16:31], v[168:171], v[164:167], v[16:31]
	v_add_u32_e32 v223, s75, v219
	v_add_u32_e32 v225, s75, v221
	v_add_u32_e32 v224, s75, v220
	v_add_u32_e32 v226, s75, v222
	s_waitcnt lgkmcnt(2)
	v_mfma_f32_32x32x16_bf16 v[32:47], v[172:175], v[160:163], v[32:47]
	v_mfma_f32_32x32x16_bf16 v[48:63], v[172:175], v[164:167], v[48:63]
	s_waitcnt lgkmcnt(1)
	v_mfma_f32_32x32x16_bf16 v[64:79], v[176:179], v[160:163], v[64:79]
	v_mfma_f32_32x32x16_bf16 v[80:95], v[176:179], v[164:167], v[80:95]
	s_waitcnt lgkmcnt(0)
	v_mfma_f32_32x32x16_bf16 v[96:111], v[180:183], v[160:163], v[96:111]
	v_mfma_f32_32x32x16_bf16 v[112:127], v[180:183], v[164:167], v[112:127]
.Lmg_kloop:
	s_waitcnt vmcnt(6)
	s_barrier
	ds_read_b128 v[128:131], v225
	ds_read_b128 v[132:135], v225 offset:6144
	ds_read_b128 v[144:147], v223
	ds_read_b128 v[148:151], v223 offset:2048
	ds_read_b128 v[152:155], v223 offset:6144
	ds_read_b128 v[156:159], v223 offset:8192
	ds_read_b128 v[160:163], v226
	ds_read_b128 v[164:167], v226 offset:6144
	ds_read_b128 v[168:171], v224
	ds_read_b128 v[172:175], v224 offset:2048
	ds_read_b128 v[176:179], v224 offset:6144
	ds_read_b128 v[180:183], v224 offset:8192
	s_mov_b32 m0, s74
	s_nop 0
	global_load_lds_dwordx4 v213, s[70:71] offset:0
	global_load_lds_dwordx4 v214, s[70:71] offset:1024
	global_load_lds_dwordx4 v215, s[70:71] offset:2048
	global_load_lds_dwordx4 v216, s[70:71] offset:3072
	s_add_u32 m0, s74, 0x1000
	s_nop 0
	global_load_lds_dwordx4 v217, s[72:73] offset:0
	global_load_lds_dwordx4 v218, s[72:73] offset:1024
	s_add_u32 s70, s70, 64
	s_addc_u32 s71, s71, 0
	s_add_u32 s72, s72, 64
	s_addc_u32 s73, s73, 0
	s_add_u32 s74, s74, 0x6000
	s_sub_u32 s1, s74, 0x12000
	s_add_u32 s0, s80, 0x12000
	s_cmp_ge_u32 s74, s0
	s_cselect_b32 s74, s1, s74
	s_add_u32 s75, s75, 0x6000
	s_cmp_eq_u32 s75, 0x12000
	s_cselect_b32 s75, 0, s75
	s_waitcnt lgkmcnt(9)
	v_mfma_f32_32x32x16_bf16 v[0:15], v[144:147], v[128:131], v[0:15]
	v_mfma_f32_32x32x16_bf16 v[16:31], v[144:147], v[132:135], v[16:31]
	s_waitcnt lgkmcnt(8)
	v_mfma_f32_32x32x16_bf16 v[32:47], v[148:151], v[128:131], v[32:47]
	v_mfma_f32_32x32x16_bf16 v[48:63], v[148:151], v[132:135], v[48:63]
	s_waitcnt lgkmcnt(7)
	v_mfma_f32_32x32x16_bf16 v[64:79], v[152:155], v[128:131], v[64:79]
	v_mfma_f32_32x32x16_bf16 v[80:95], v[152:155], v[132:135], v[80:95]
	s_waitcnt lgkmcnt(6)
	v_mfma_f32_32x32x16_bf16 v[96:111], v[156:159], v[128:131], v[96:111]
	v_mfma_f32_32x32x16_bf16 v[112:127], v[156:159], v[132:135], v[112:127]
	s_waitcnt lgkmcnt(3)
	v_mfma_f32_32x32x16_bf16 v[0:15], v[168:171], v[160:163], v[0:15]
	v_mfma_f32_32x32x16_bf16 v[16:31], v[168:171], v[164:167], v[16:31]
	v_add_u32_e32 v223, s75, v219
	v_add_u32_e32 v225, s75, v221
	v_add_u32_e32 v224, s75, v220
	v_add_u32_e32 v226, s75, v222
	s_waitcnt lgkmcnt(2)
	v_mfma_f32_32x32x16_bf16 v[32:47], v[172:175], v[160:163], v[32:47]
	v_mfma_f32_32x32x16_bf16 v[48:63], v[172:175], v[164:167], v[48:63]
	s_waitcnt lgkmcnt(1)
	v_mfma_f32_32x32x16_bf16 v[64:79], v[176:179], v[160:163], v[64:79]
	v_mfma_f32_32x32x16_bf16 v[80:95], v[176:179], v[164:167], v[80:95]
	s_waitcnt lgkmcnt(0)
	v_mfma_f32_32x32x16_bf16 v[96:111], v[180:183], v[160:163], v[96:111]
	v_mfma_f32_32x32x16_bf16 v[112:127], v[180:183], v[164:167], v[112:127]
	s_sub_u32 s76, s76, 1
	s_cmp_lg_u32 s76, 0
	s_cbranch_scc1 .Lmg_kloop
; DI unsigned pack2(float lo, float hi) { f32x2_t v = {lo, hi}; bf16x2_t r = __builtin_convertvector(v, bf16x2_t); return __builtin_bit_cast(unsigned, r); }
; template <int EPI>
; DI void epilogue(const Params& p, int layer, f32x16 (&acc)[2][2], int mrow0, int ncol0, int lane) {
;     ...
;   if (EPI == EPI_U) {
;     if (ncol0 < 768 && mrow0 < NLAT) {
;       bf16_t* HT = (bf16_t*)(p.ws + OFF_HT);
; #pragma unroll
;       for (int ni = 0; ni < 2; ++ni) {
;         const int col = ncol0 + ni * 32 + c, which = col >> 8, ch = col & 255;
; #pragma unroll
;         for (int mi = 0; mi < 2; ++mi)
; #pragma unroll
;           for (int g = 0; g < 4; ++g) {
;             const int row0 = mrow0 + mi * 32 + 8 * g + 4 * h, bq = row0 >> 12, s0 = row0 & 4095;
;             uint2 w;
;             w.x = pack2(acc[mi][ni][4 * g], acc[mi][ni][4 * g + 1]);
;             w.y = pack2(acc[mi][ni][4 * g + 2], acc[mi][ni][4 * g + 3]);
;             *(uint2*)(HT + (((size_t)which * NB + bq) * 256 + ch) * SEQ + s0) = w;
;           }
;       }
;     } else if (ncol0 >= 1280 && ncol0 < 1408) {
;       bf16_t* Vgt = (bf16_t*)(p.ws + OFF_VGT);
;       const int kh = (ncol0 - 1280) >> 6;
; #pragma unroll
;       for (int ni = 0; ni < 2; ++ni) {
;         const int dv = ni * 32 + c;
; #pragma unroll
;         for (int mi = 0; mi < 2; ++mi)
; #pragma unroll
;           for (int g = 0; g < 4; ++g) {
;             int bq, kp; row_info(mrow0 + mi * 32 + 8 * g + 4 * h, bq, kp);
;             uint2 w;
;             w.x = pack2(acc[mi][ni][4 * g], acc[mi][ni][4 * g + 1]);
;             w.y = pack2(acc[mi][ni][4 * g + 2], acc[mi][ni][4 * g + 3]);
;             *(uint2*)(Vgt + ((size_t)(bq * 2 + kh) * 64 + dv) * NKEY + kp) = w;
; template <int EPI>
; DI void gemm_phase(const Params& p, int layer, const bf16_t* __restrict__ A, int lda, const bf16_t* __restrict__ Bt, int ldb, int K, int MT, int NT,
;                    char* smem, bool rev = false) {
;     ...
;     for (int kt = 0; kt < nk; kt += 2) {
;       G_COMPUTE(0)
;       G_WRITE(q, 1)
;       __syncthreads();
;       if (kt + 3 < nk) G_LOAD(q, (kt + 3) << 6)
;       G_COMPUTE(1)
;       if (kt + 2 < nk) G_WRITE(p, 0)
;       __syncthreads();
;       if (kt + 4 < nk) G_LOAD(p, (kt + 4) << 6)
;     }
	s_waitcnt vmcnt(6)
	s_barrier
	ds_read_b128 v[128:131], v225
	ds_read_b128 v[132:135], v225 offset:6144
	ds_read_b128 v[144:147], v223
	ds_read_b128 v[148:151], v223 offset:2048
	ds_read_b128 v[152:155], v223 offset:6144
	ds_read_b128 v[156:159], v223 offset:8192
	ds_read_b128 v[160:163], v226
	ds_read_b128 v[164:167], v226 offset:6144
	ds_read_b128 v[168:171], v224
	ds_read_b128 v[172:175], v224 offset:2048
	ds_read_b128 v[176:179], v224 offset:6144
	ds_read_b128 v[180:183], v224 offset:8192
	s_add_u32 s75, s75, 0x6000
	s_cmp_eq_u32 s75, 0x12000
	s_cselect_b32 s75, 0, s75
	s_waitcnt lgkmcnt(9)
	v_mfma_f32_32x32x16_bf16 v[0:15], v[144:147], v[128:131], v[0:15]
	v_mfma_f32_32x32x16_bf16 v[16:31], v[144:147], v[132:135], v[16:31]
	s_waitcnt lgkmcnt(8)
	v_mfma_f32_32x32x16_bf16 v[32:47], v[148:151], v[128:131], v[32:47]
	v_mfma_f32_32x32x16_bf16 v[48:63], v[148:151], v[132:135], v[48:63]
	s_waitcnt lgkmcnt(7)
	v_mfma_f32_32x32x16_bf16 v[64:79], v[152:155], v[128:131], v[64:79]
	v_mfma_f32_32x32x16_bf16 v[80:95], v[152:155], v[132:135], v[80:95]
	s_waitcnt lgkmcnt(6)
	v_mfma_f32_32x32x16_bf16 v[96:111], v[156:159], v[128:131], v[96:111]
	v_mfma_f32_32x32x16_bf16 v[112:127], v[156:159], v[132:135], v[112:127]
	s_waitcnt lgkmcnt(3)
	v_mfma_f32_32x32x16_bf16 v[0:15], v[168:171], v[160:163], v[0:15]
	v_mfma_f32_32x32x16_bf16 v[16:31], v[168:171], v[164:167], v[16:31]
	v_add_u32_e32 v223, s75, v219
	v_add_u32_e32 v225, s75, v221
	v_add_u32_e32 v224, s75, v220
	v_add_u32_e32 v226, s75, v222
	s_waitcnt lgkmcnt(2)
	v_mfma_f32_32x32x16_bf16 v[32:47], v[172:175], v[160:163], v[32:47]
	v_mfma_f32_32x32x16_bf16 v[48:63], v[172:175], v[164:167], v[48:63]
	s_waitcnt lgkmcnt(1)
	v_mfma_f32_32x32x16_bf16 v[64:79], v[176:179], v[160:163], v[64:79]
	v_mfma_f32_32x32x16_bf16 v[80:95], v[176:179], v[164:167], v[80:95]
	s_waitcnt lgkmcnt(0)
	v_mfma_f32_32x32x16_bf16 v[96:111], v[180:183], v[160:163], v[96:111]
	v_mfma_f32_32x32x16_bf16 v[112:127], v[180:183], v[164:167], v[112:127]
	s_waitcnt vmcnt(0)
	s_barrier
	ds_read_b128 v[128:131], v225
	ds_read_b128 v[132:135], v225 offset:6144
	ds_read_b128 v[144:147], v223
	ds_read_b128 v[148:151], v223 offset:2048
	ds_read_b128 v[152:155], v223 offset:6144
	ds_read_b128 v[156:159], v223 offset:8192
	ds_read_b128 v[160:163], v226
	ds_read_b128 v[164:167], v226 offset:6144
	ds_read_b128 v[168:171], v224
	ds_read_b128 v[172:175], v224 offset:2048
	ds_read_b128 v[176:179], v224 offset:6144
	ds_read_b128 v[180:183], v224 offset:8192
	s_add_u32 s75, s75, 0x6000
	s_cmp_eq_u32 s75, 0x12000
	s_cselect_b32 s75, 0, s75
	s_waitcnt lgkmcnt(9)
	v_mfma_f32_32x32x16_bf16 v[0:15], v[144:147], v[128:131], v[0:15]
	v_mfma_f32_32x32x16_bf16 v[16:31], v[144:147], v[132:135], v[16:31]
	s_waitcnt lgkmcnt(8)
	v_mfma_f32_32x32x16_bf16 v[32:47], v[148:151], v[128:131], v[32:47]
	v_mfma_f32_32x32x16_bf16 v[48:63], v[148:151], v[132:135], v[48:63]
	s_waitcnt lgkmcnt(7)
	v_mfma_f32_32x32x16_bf16 v[64:79], v[152:155], v[128:131], v[64:79]
	v_mfma_f32_32x32x16_bf16 v[80:95], v[152:155], v[132:135], v[80:95]
	s_waitcnt lgkmcnt(6)
	v_mfma_f32_32x32x16_bf16 v[96:111], v[156:159], v[128:131], v[96:111]
	v_mfma_f32_32x32x16_bf16 v[112:127], v[156:159], v[132:135], v[112:127]
	s_waitcnt lgkmcnt(3)
	v_mfma_f32_32x32x16_bf16 v[0:15], v[168:171], v[160:163], v[0:15]
	v_mfma_f32_32x32x16_bf16 v[16:31], v[168:171], v[164:167], v[16:31]
	v_add_u32_e32 v223, s75, v219
	v_add_u32_e32 v225, s75, v221
	v_add_u32_e32 v224, s75, v220
	v_add_u32_e32 v226, s75, v222
	s_waitcnt lgkmcnt(2)
	v_mfma_f32_32x32x16_bf16 v[32:47], v[172:175], v[160:163], v[32:47]
	v_mfma_f32_32x32x16_bf16 v[48:63], v[172:175], v[164:167], v[48:63]
	s_waitcnt lgkmcnt(1)
	v_mfma_f32_32x32x16_bf16 v[64:79], v[176:179], v[160:163], v[64:79]
	v_mfma_f32_32x32x16_bf16 v[80:95], v[176:179], v[164:167], v[80:95]
	s_waitcnt lgkmcnt(0)
	v_mfma_f32_32x32x16_bf16 v[96:111], v[180:183], v[160:163], v[96:111]
	v_mfma_f32_32x32x16_bf16 v[112:127], v[180:183], v[164:167], v[112:127]
.Lmg_dbg_epi:
	s_nop 15
	s_nop 3
	s_cmp_eq_u32 s52, 1
	s_cbranch_scc1 .Lmg_epi1
	s_cmp_eq_u32 s52, 2
	s_cbranch_scc1 .Lmg_epi2
	s_cmp_eq_u32 s52, 3
	s_cbranch_scc1 .Lmg_epi3
	s_lshl_b32 s90, s78, 7
	s_add_u32 s90, s90, s67
	s_lshl_b32 s91, s79, 6
	s_add_u32 s91, s91, s68
	s_cmp_lt_u32 s91, 768
	s_cbranch_scc0 .Lmg_uvgt_9
	s_cmp_lt_u32 s67, 0x8000
	s_cbranch_scc0 .Lmg_uplain_8
	s_lshr_b32 s0, s91, 8
	s_lshl_b32 s0, s0, 3
	s_lshr_b32 s1, s67, 12
	s_add_u32 s0, s0, s1
	s_lshl_b32 s0, s0, 21
	s_add_u32 s0, s0, 0x12980000
	s_add_u32 s82, s24, s0
	s_addc_u32 s83, s25, 0
	s_and_b32 s10, s91, 255
	s_and_b32 s11, s67, 0xfff
	s_lshl_b32 s12, s78, 7
	s_add_u32 s11, s11, s12
	s_movk_i32 s13, 0x2000
	s_branch .Lmg_utr_10
.Lmg_uvgt_9:
	s_cmp_ge_u32 s91, 1280
	s_cbranch_scc0 .Lmg_uplain_8
	s_cmp_lt_u32 s91, 1408
	s_cbranch_scc0 .Lmg_uplain_8
	s_sub_u32 s0, s91, 1280
	s_lshr_b32 s0, s0, 6
	s_cmp_lt_u32 s67, 0x8000
	s_cbranch_scc0 .Lmg_vctx_11
	s_lshr_b32 s1, s67, 12
	s_and_b32 s11, s67, 0xfff
	s_add_u32 s11, s11, 256
	s_branch .Lmg_vj_12
.Lmg_vctx_11:
	s_sub_u32 s1, s67, 0x8000
	s_lshr_b32 s1, s1, 8
	s_mov_b32 s11, 0
.Lmg_vj_12:
	s_lshl_b32 s1, s1, 1
	s_add_u32 s1, s1, s0
	s_mul_i32 s1, s1, 0x88000
	s_add_u32 s1, s1, 0xa180000
	s_add_u32 s82, s24, s1
	s_addc_u32 s83, s25, 0
	s_mov_b32 s10, 0
	s_lshl_b32 s12, s78, 7
	s_add_u32 s11, s11, s12
	s_movk_i32 s13, 0x2200
; DI unsigned pack2(float lo, float hi) { f32x2_t v = {lo, hi}; bf16x2_t r = __builtin_convertvector(v, bf16x2_t); return __builtin_bit_cast(unsigned, r); }
; template <int EPI>
; DI void epilogue(const Params& p, int layer, f32x16 (&acc)[2][2], int mrow0, int ncol0, int lane) {
;     ...
;   if (EPI == EPI_U) {
;     if (ncol0 < 768 && mrow0 < NLAT) {
;       bf16_t* HT = (bf16_t*)(p.ws + OFF_HT);
; #pragma unroll
;       for (int ni = 0; ni < 2; ++ni) {
;         const int col = ncol0 + ni * 32 + c, which = col >> 8, ch = col & 255;
; #pragma unroll
;         for (int mi = 0; mi < 2; ++mi)
; #pragma unroll
;           for (int g = 0; g < 4; ++g) {
;             const int row0 = mrow0 + mi * 32 + 8 * g + 4 * h, bq = row0 >> 12, s0 = row0 & 4095;
;             uint2 w;
;             w.x = pack2(acc[mi][ni][4 * g], acc[mi][ni][4 * g + 1]);
;             w.y = pack2(acc[mi][ni][4 * g + 2], acc[mi][ni][4 * g + 3]);
;             *(uint2*)(HT + (((size_t)which * NB + bq) * 256 + ch) * SEQ + s0) = w;
;           }
;       }
;     } else if (ncol0 >= 1280 && ncol0 < 1408) {
;       bf16_t* Vgt = (bf16_t*)(p.ws + OFF_VGT);
;       const int kh = (ncol0 - 1280) >> 6;
; #pragma unroll
;       for (int ni = 0; ni < 2; ++ni) {
;         const int dv = ni * 32 + c;
; #pragma unroll
;         for (int mi = 0; mi < 2; ++mi)
; #pragma unroll
;           for (int g = 0; g < 4; ++g) {
;             int bq, kp; row_info(mrow0 + mi * 32 + 8 * g + 4 * h, bq, kp);
;             uint2 w;
;             w.x = pack2(acc[mi][ni][4 * g], acc[mi][ni][4 * g + 1]);
;             w.y = pack2(acc[mi][ni][4 * g + 2], acc[mi][ni][4 * g + 3]);
;             *(uint2*)(Vgt + ((size_t)(bq * 2 + kh) * 64 + dv) * NKEY + kp) = w;
;           }
;       }
.Lmg_utr_10:
	v_add_u32_e32 v184, s10, v227
	v_mul_lo_u32 v184, v184, s13
	v_lshl_add_u32 v185, v228, 2, s11
	v_lshl_add_u32 v229, v185, 1, v184
	s_lshl_b32 s28, s13, 5
	v_add_u32_e32 v230, s28, v229
	v_cvt_pk_bf16_f32 v144, v0, v1
	v_cvt_pk_bf16_f32 v145, v2, v3
	global_store_dwordx2 v229, v[144:145], s[82:83]
	v_cvt_pk_bf16_f32 v146, v4, v5
	v_cvt_pk_bf16_f32 v147, v6, v7
	global_store_dwordx2 v229, v[146:147], s[82:83] offset:16
	v_cvt_pk_bf16_f32 v148, v8, v9
	v_cvt_pk_bf16_f32 v149, v10, v11
	global_store_dwordx2 v229, v[148:149], s[82:83] offset:32
	v_cvt_pk_bf16_f32 v150, v12, v13
	v_cvt_pk_bf16_f32 v151, v14, v15
	global_store_dwordx2 v229, v[150:151], s[82:83] offset:48
	v_cvt_pk_bf16_f32 v152, v32, v33
	v_cvt_pk_bf16_f32 v153, v34, v35
	global_store_dwordx2 v229, v[152:153], s[82:83] offset:64
	v_cvt_pk_bf16_f32 v154, v36, v37
	v_cvt_pk_bf16_f32 v155, v38, v39
	global_store_dwordx2 v229, v[154:155], s[82:83] offset:80
	v_cvt_pk_bf16_f32 v156, v40, v41
	v_cvt_pk_bf16_f32 v157, v42, v43
	global_store_dwordx2 v229, v[156:157], s[82:83] offset:96
	v_cvt_pk_bf16_f32 v158, v44, v45
	v_cvt_pk_bf16_f32 v159, v46, v47
	global_store_dwordx2 v229, v[158:159], s[82:83] offset:112
	v_cvt_pk_bf16_f32 v144, v64, v65
	v_cvt_pk_bf16_f32 v145, v66, v67
	global_store_dwordx2 v229, v[144:145], s[82:83] offset:128
	v_cvt_pk_bf16_f32 v146, v68, v69
	v_cvt_pk_bf16_f32 v147, v70, v71
	global_store_dwordx2 v229, v[146:147], s[82:83] offset:144
	v_cvt_pk_bf16_f32 v148, v72, v73
	v_cvt_pk_bf16_f32 v149, v74, v75
	global_store_dwordx2 v229, v[148:149], s[82:83] offset:160
	v_cvt_pk_bf16_f32 v150, v76, v77
	v_cvt_pk_bf16_f32 v151, v78, v79
	global_store_dwordx2 v229, v[150:151], s[82:83] offset:176
	v_cvt_pk_bf16_f32 v152, v96, v97
	v_cvt_pk_bf16_f32 v153, v98, v99
	global_store_dwordx2 v229, v[152:153], s[82:83] offset:192
	v_cvt_pk_bf16_f32 v154, v100, v101
	v_cvt_pk_bf16_f32 v155, v102, v103
	global_store_dwordx2 v229, v[154:155], s[82:83] offset:208
	v_cvt_pk_bf16_f32 v156, v104, v105
	v_cvt_pk_bf16_f32 v157, v106, v107
	global_store_dwordx2 v229, v[156:157], s[82:83] offset:224
	v_cvt_pk_bf16_f32 v158, v108, v109
	v_cvt_pk_bf16_f32 v159, v110, v111
	global_store_dwordx2 v229, v[158:159], s[82:83] offset:240
	v_cvt_pk_bf16_f32 v144, v16, v17
	v_cvt_pk_bf16_f32 v145, v18, v19
	global_store_dwordx2 v230, v[144:145], s[82:83]
	v_cvt_pk_bf16_f32 v146, v20, v21
	v_cvt_pk_bf16_f32 v147, v22, v23
	global_store_dwordx2 v230, v[146:147], s[82:83] offset:16
	v_cvt_pk_bf16_f32 v148, v24, v25
	v_cvt_pk_bf16_f32 v149, v26, v27
	global_store_dwordx2 v230, v[148:149], s[82:83] offset:32
	v_cvt_pk_bf16_f32 v150, v28, v29
	v_cvt_pk_bf16_f32 v151, v30, v31
	global_store_dwordx2 v230, v[150:151], s[82:83] offset:48
	v_cvt_pk_bf16_f32 v152, v48, v49
	v_cvt_pk_bf16_f32 v153, v50, v51
	global_store_dwordx2 v230, v[152:153], s[82:83] offset:64
	v_cvt_pk_bf16_f32 v154, v52, v53
	v_cvt_pk_bf16_f32 v155, v54, v55
	global_store_dwordx2 v230, v[154:155], s[82:83] offset:80
	v_cvt_pk_bf16_f32 v156, v56, v57
	v_cvt_pk_bf16_f32 v157, v58, v59
	global_store_dwordx2 v230, v[156:157], s[82:83] offset:96
	v_cvt_pk_bf16_f32 v158, v60, v61
	v_cvt_pk_bf16_f32 v159, v62, v63
	global_store_dwordx2 v230, v[158:159], s[82:83] offset:112
	v_cvt_pk_bf16_f32 v144, v80, v81
	v_cvt_pk_bf16_f32 v145, v82, v83
	global_store_dwordx2 v230, v[144:145], s[82:83] offset:128
	v_cvt_pk_bf16_f32 v146, v84, v85
	v_cvt_pk_bf16_f32 v147, v86, v87
	global_store_dwordx2 v230, v[146:147], s[82:83] offset:144
	v_cvt_pk_bf16_f32 v148, v88, v89
	v_cvt_pk_bf16_f32 v149, v90, v91
	global_store_dwordx2 v230, v[148:149], s[82:83] offset:160
	v_cvt_pk_bf16_f32 v150, v92, v93
	v_cvt_pk_bf16_f32 v151, v94, v95
	global_store_dwordx2 v230, v[150:151], s[82:83] offset:176
	v_cvt_pk_bf16_f32 v152, v112, v113
	v_cvt_pk_bf16_f32 v153, v114, v115
	global_store_dwordx2 v230, v[152:153], s[82:83] offset:192
	v_cvt_pk_bf16_f32 v154, v116, v117
	v_cvt_pk_bf16_f32 v155, v118, v119
	global_store_dwordx2 v230, v[154:155], s[82:83] offset:208
	v_cvt_pk_bf16_f32 v156, v120, v121
	v_cvt_pk_bf16_f32 v157, v122, v123
	global_store_dwordx2 v230, v[156:157], s[82:83] offset:224
	v_cvt_pk_bf16_f32 v158, v124, v125
	v_cvt_pk_bf16_f32 v159, v126, v127
	global_store_dwordx2 v230, v[158:159], s[82:83] offset:240
	s_branch .Lmg_next
; DI bf16_t f2bf(float x) { return (bf16_t)(pack2(x, x) & 0xffffu); }
; DI int crow(int reg, int h) { return (reg & 3) + 8 * (reg >> 2) + 4 * h; }
; template <int EPI>
; DI void epilogue(const Params& p, int layer, f32x16 (&acc)[2][2], int mrow0, int ncol0, int lane) {
;     ...
;     } else {
;       bf16_t* U = (bf16_t*)(p.ws + OFF_U);
; #pragma unroll
;       for (int mi = 0; mi < 2; ++mi)
; #pragma unroll
;         for (int ni = 0; ni < 2; ++ni)
; #pragma unroll
;           for (int r = 0; r < 16; ++r) {
;             int row = mrow0 + mi * 32 + crow(r, h), col = ncol0 + ni * 32 + c;
;             U[(size_t)row * INP + col] = f2bf(acc[mi][ni][r]);
;           }
.Lmg_uplain_8:
	v_lshl_add_u32 v184, v228, 2, s90
	s_movk_i32 s0, 3840
	v_mul_lo_u32 v184, v184, s0
	v_add_u32_e32 v185, s91, v227
	v_lshl_add_u32 v229, v185, 1, v184
	s_mov_b32 s82, s24
	s_mov_b32 s83, s25
	v_mov_b32_e32 v152, v229
	v_add_u32_e32 v153, 0xf00, v229
	v_cvt_pk_bf16_f32 v144, v0, v1
	global_store_short v152, v144, s[82:83]
	global_store_short_d16_hi v153, v144, s[82:83]
	v_cvt_pk_bf16_f32 v145, v16, v17
	global_store_short v152, v145, s[82:83] offset:64
	global_store_short_d16_hi v153, v145, s[82:83] offset:64
	v_add_u32_e32 v154, 0x1e00, v229
	v_add_u32_e32 v155, 0x2d00, v229
	v_cvt_pk_bf16_f32 v146, v2, v3
	global_store_short v154, v146, s[82:83]
	global_store_short_d16_hi v155, v146, s[82:83]
	v_cvt_pk_bf16_f32 v147, v18, v19
	global_store_short v154, v147, s[82:83] offset:64
	global_store_short_d16_hi v155, v147, s[82:83] offset:64
	v_add_u32_e32 v156, 0x7800, v229
	v_add_u32_e32 v157, 0x8700, v229
	v_cvt_pk_bf16_f32 v148, v4, v5
	global_store_short v156, v148, s[82:83]
	global_store_short_d16_hi v157, v148, s[82:83]
	v_cvt_pk_bf16_f32 v149, v20, v21
	global_store_short v156, v149, s[82:83] offset:64
	global_store_short_d16_hi v157, v149, s[82:83] offset:64
	v_add_u32_e32 v158, 0x9600, v229
	v_add_u32_e32 v159, 0xa500, v229
	v_cvt_pk_bf16_f32 v150, v6, v7
	global_store_short v158, v150, s[82:83]
	global_store_short_d16_hi v159, v150, s[82:83]
	v_cvt_pk_bf16_f32 v151, v22, v23
	global_store_short v158, v151, s[82:83] offset:64
	global_store_short_d16_hi v159, v151, s[82:83] offset:64
	v_add_u32_e32 v152, 0xf000, v229
	v_add_u32_e32 v153, 0xff00, v229
	v_cvt_pk_bf16_f32 v144, v8, v9
	global_store_short v152, v144, s[82:83]
	global_store_short_d16_hi v153, v144, s[82:83]
	v_cvt_pk_bf16_f32 v145, v24, v25
	global_store_short v152, v145, s[82:83] offset:64
	global_store_short_d16_hi v153, v145, s[82:83] offset:64
	v_add_u32_e32 v154, 0x10e00, v229
	v_add_u32_e32 v155, 0x11d00, v229
	v_cvt_pk_bf16_f32 v146, v10, v11
	global_store_short v154, v146, s[82:83]
	global_store_short_d16_hi v155, v146, s[82:83]
	v_cvt_pk_bf16_f32 v147, v26, v27
	global_store_short v154, v147, s[82:83] offset:64
	global_store_short_d16_hi v155, v147, s[82:83] offset:64
	v_add_u32_e32 v156, 0x16800, v229
	v_add_u32_e32 v157, 0x17700, v229
	v_cvt_pk_bf16_f32 v148, v12, v13
	global_store_short v156, v148, s[82:83]
	global_store_short_d16_hi v157, v148, s[82:83]
	v_cvt_pk_bf16_f32 v149, v28, v29
	global_store_short v156, v149, s[82:83] offset:64
	global_store_short_d16_hi v157, v149, s[82:83] offset:64
	v_add_u32_e32 v158, 0x18600, v229
	v_add_u32_e32 v159, 0x19500, v229
	v_cvt_pk_bf16_f32 v150, v14, v15
	global_store_short v158, v150, s[82:83]
	global_store_short_d16_hi v159, v150, s[82:83]
	v_cvt_pk_bf16_f32 v151, v30, v31
	global_store_short v158, v151, s[82:83] offset:64
	global_store_short_d16_hi v159, v151, s[82:83] offset:64
	v_add_u32_e32 v152, 0x1e000, v229
	v_add_u32_e32 v153, 0x1ef00, v229
	v_cvt_pk_bf16_f32 v144, v32, v33
	global_store_short v152, v144, s[82:83]
	global_store_short_d16_hi v153, v144, s[82:83]
	v_cvt_pk_bf16_f32 v145, v48, v49
	global_store_short v152, v145, s[82:83] offset:64
	global_store_short_d16_hi v153, v145, s[82:83] offset:64
	v_add_u32_e32 v154, 0x1fe00, v229
	v_add_u32_e32 v155, 0x20d00, v229
	v_cvt_pk_bf16_f32 v146, v34, v35
	global_store_short v154, v146, s[82:83]
	global_store_short_d16_hi v155, v146, s[82:83]
	v_cvt_pk_bf16_f32 v147, v50, v51
	global_store_short v154, v147, s[82:83] offset:64
	global_store_short_d16_hi v155, v147, s[82:83] offset:64
	v_add_u32_e32 v156, 0x25800, v229
	v_add_u32_e32 v157, 0x26700, v229
	v_cvt_pk_bf16_f32 v148, v36, v37
	global_store_short v156, v148, s[82:83]
	global_store_short_d16_hi v157, v148, s[82:83]
	v_cvt_pk_bf16_f32 v149, v52, v53
	global_store_short v156, v149, s[82:83] offset:64
	global_store_short_d16_hi v157, v149, s[82:83] offset:64
	v_add_u32_e32 v158, 0x27600, v229
	v_add_u32_e32 v159, 0x28500, v229
	v_cvt_pk_bf16_f32 v150, v38, v39
	global_store_short v158, v150, s[82:83]
	global_store_short_d16_hi v159, v150, s[82:83]
	v_cvt_pk_bf16_f32 v151, v54, v55
	global_store_short v158, v151, s[82:83] offset:64
	global_store_short_d16_hi v159, v151, s[82:83] offset:64
	v_add_u32_e32 v152, 0x2d000, v229
	v_add_u32_e32 v153, 0x2df00, v229
	v_cvt_pk_bf16_f32 v144, v40, v41
	global_store_short v152, v144, s[82:83]
	global_store_short_d16_hi v153, v144, s[82:83]
	v_cvt_pk_bf16_f32 v145, v56, v57
	global_store_short v152, v145, s[82:83] offset:64
	global_store_short_d16_hi v153, v145, s[82:83] offset:64
	v_add_u32_e32 v154, 0x2ee00, v229
	v_add_u32_e32 v155, 0x2fd00, v229
	v_cvt_pk_bf16_f32 v146, v42, v43
	global_store_short v154, v146, s[82:83]
	global_store_short_d16_hi v155, v146, s[82:83]
	v_cvt_pk_bf16_f32 v147, v58, v59
	global_store_short v154, v147, s[82:83] offset:64
	global_store_short_d16_hi v155, v147, s[82:83] offset:64
	v_add_u32_e32 v156, 0x34800, v229
	v_add_u32_e32 v157, 0x35700, v229
	v_cvt_pk_bf16_f32 v148, v44, v45
	global_store_short v156, v148, s[82:83]
	global_store_short_d16_hi v157, v148, s[82:83]
	v_cvt_pk_bf16_f32 v149, v60, v61
	global_store_short v156, v149, s[82:83] offset:64
	global_store_short_d16_hi v157, v149, s[82:83] offset:64
	v_add_u32_e32 v158, 0x36600, v229
	v_add_u32_e32 v159, 0x37500, v229
	v_cvt_pk_bf16_f32 v150, v46, v47
	global_store_short v158, v150, s[82:83]
	global_store_short_d16_hi v159, v150, s[82:83]
	v_cvt_pk_bf16_f32 v151, v62, v63
	global_store_short v158, v151, s[82:83] offset:64
	global_store_short_d16_hi v159, v151, s[82:83] offset:64
	v_add_u32_e32 v152, 0x3c000, v229
	v_add_u32_e32 v153, 0x3cf00, v229
; DI bf16_t f2bf(float x) { return (bf16_t)(pack2(x, x) & 0xffffu); }
; DI int crow(int reg, int h) { return (reg & 3) + 8 * (reg >> 2) + 4 * h; }
; template <int EPI>
; DI void epilogue(const Params& p, int layer, f32x16 (&acc)[2][2], int mrow0, int ncol0, int lane) {
;     ...
;       bf16_t* U = (bf16_t*)(p.ws + OFF_U);
; #pragma unroll
;       for (int mi = 0; mi < 2; ++mi)
; #pragma unroll
;         for (int ni = 0; ni < 2; ++ni)
; #pragma unroll
;           for (int r = 0; r < 16; ++r) {
;             int row = mrow0 + mi * 32 + crow(r, h), col = ncol0 + ni * 32 + c;
;             U[(size_t)row * INP + col] = f2bf(acc[mi][ni][r]);
;           }
;     }
;   } else if (EPI == EPI_RES1 || EPI == EPI_RES2) {
;     const float* mod = (const float*)(p.ws + OFF_MOD) + (size_t)layer * 9 * 6144;
;     const int b9 = mrow0 < NLAT ? (mrow0 >> 12) : 8;
;     const int gsel = (EPI == EPI_RES1) ? 2 : 5;
;     const bool first = (EPI == EPI_RES1) && layer == 0;
;     const float* xo_base = xold_ptr(p, layer, first, mrow0) + (ncol0 + c);
;     float* xn_base = xnew_ptr(p, mrow0) + (ncol0 + c);
	v_cvt_pk_bf16_f32 v144, v64, v65
	global_store_short v152, v144, s[82:83]
	global_store_short_d16_hi v153, v144, s[82:83]
	v_cvt_pk_bf16_f32 v145, v80, v81
	global_store_short v152, v145, s[82:83] offset:64
	global_store_short_d16_hi v153, v145, s[82:83] offset:64
	v_add_u32_e32 v154, 0x3de00, v229
	v_add_u32_e32 v155, 0x3ed00, v229
	v_cvt_pk_bf16_f32 v146, v66, v67
	global_store_short v154, v146, s[82:83]
	global_store_short_d16_hi v155, v146, s[82:83]
	v_cvt_pk_bf16_f32 v147, v82, v83
	global_store_short v154, v147, s[82:83] offset:64
	global_store_short_d16_hi v155, v147, s[82:83] offset:64
	v_add_u32_e32 v156, 0x43800, v229
	v_add_u32_e32 v157, 0x44700, v229
	v_cvt_pk_bf16_f32 v148, v68, v69
	global_store_short v156, v148, s[82:83]
	global_store_short_d16_hi v157, v148, s[82:83]
	v_cvt_pk_bf16_f32 v149, v84, v85
	global_store_short v156, v149, s[82:83] offset:64
	global_store_short_d16_hi v157, v149, s[82:83] offset:64
	v_add_u32_e32 v158, 0x45600, v229
	v_add_u32_e32 v159, 0x46500, v229
	v_cvt_pk_bf16_f32 v150, v70, v71
	global_store_short v158, v150, s[82:83]
	global_store_short_d16_hi v159, v150, s[82:83]
	v_cvt_pk_bf16_f32 v151, v86, v87
	global_store_short v158, v151, s[82:83] offset:64
	global_store_short_d16_hi v159, v151, s[82:83] offset:64
	v_add_u32_e32 v152, 0x4b000, v229
	v_add_u32_e32 v153, 0x4bf00, v229
	v_cvt_pk_bf16_f32 v144, v72, v73
	global_store_short v152, v144, s[82:83]
	global_store_short_d16_hi v153, v144, s[82:83]
	v_cvt_pk_bf16_f32 v145, v88, v89
	global_store_short v152, v145, s[82:83] offset:64
	global_store_short_d16_hi v153, v145, s[82:83] offset:64
	v_add_u32_e32 v154, 0x4ce00, v229
	v_add_u32_e32 v155, 0x4dd00, v229
	v_cvt_pk_bf16_f32 v146, v74, v75
	global_store_short v154, v146, s[82:83]
	global_store_short_d16_hi v155, v146, s[82:83]
	v_cvt_pk_bf16_f32 v147, v90, v91
	global_store_short v154, v147, s[82:83] offset:64
	global_store_short_d16_hi v155, v147, s[82:83] offset:64
	v_add_u32_e32 v156, 0x52800, v229
	v_add_u32_e32 v157, 0x53700, v229
	v_cvt_pk_bf16_f32 v148, v76, v77
	global_store_short v156, v148, s[82:83]
	global_store_short_d16_hi v157, v148, s[82:83]
	v_cvt_pk_bf16_f32 v149, v92, v93
	global_store_short v156, v149, s[82:83] offset:64
	global_store_short_d16_hi v157, v149, s[82:83] offset:64
	v_add_u32_e32 v158, 0x54600, v229
	v_add_u32_e32 v159, 0x55500, v229
	v_cvt_pk_bf16_f32 v150, v78, v79
	global_store_short v158, v150, s[82:83]
	global_store_short_d16_hi v159, v150, s[82:83]
	v_cvt_pk_bf16_f32 v151, v94, v95
	global_store_short v158, v151, s[82:83] offset:64
	global_store_short_d16_hi v159, v151, s[82:83] offset:64
	v_add_u32_e32 v152, 0x5a000, v229
	v_add_u32_e32 v153, 0x5af00, v229
	v_cvt_pk_bf16_f32 v144, v96, v97
	global_store_short v152, v144, s[82:83]
	global_store_short_d16_hi v153, v144, s[82:83]
	v_cvt_pk_bf16_f32 v145, v112, v113
	global_store_short v152, v145, s[82:83] offset:64
	global_store_short_d16_hi v153, v145, s[82:83] offset:64
	v_add_u32_e32 v154, 0x5be00, v229
	v_add_u32_e32 v155, 0x5cd00, v229
	v_cvt_pk_bf16_f32 v146, v98, v99
	global_store_short v154, v146, s[82:83]
	global_store_short_d16_hi v155, v146, s[82:83]
	v_cvt_pk_bf16_f32 v147, v114, v115
	global_store_short v154, v147, s[82:83] offset:64
	global_store_short_d16_hi v155, v147, s[82:83] offset:64
	v_add_u32_e32 v156, 0x61800, v229
	v_add_u32_e32 v157, 0x62700, v229
	v_cvt_pk_bf16_f32 v148, v100, v101
	global_store_short v156, v148, s[82:83]
	global_store_short_d16_hi v157, v148, s[82:83]
	v_cvt_pk_bf16_f32 v149, v116, v117
	global_store_short v156, v149, s[82:83] offset:64
	global_store_short_d16_hi v157, v149, s[82:83] offset:64
	v_add_u32_e32 v158, 0x63600, v229
	v_add_u32_e32 v159, 0x64500, v229
	v_cvt_pk_bf16_f32 v150, v102, v103
	global_store_short v158, v150, s[82:83]
	global_store_short_d16_hi v159, v150, s[82:83]
	v_cvt_pk_bf16_f32 v151, v118, v119
	global_store_short v158, v151, s[82:83] offset:64
	global_store_short_d16_hi v159, v151, s[82:83] offset:64
	v_add_u32_e32 v152, 0x69000, v229
	v_add_u32_e32 v153, 0x69f00, v229
	v_cvt_pk_bf16_f32 v144, v104, v105
	global_store_short v152, v144, s[82:83]
	global_store_short_d16_hi v153, v144, s[82:83]
	v_cvt_pk_bf16_f32 v145, v120, v121
	global_store_short v152, v145, s[82:83] offset:64
	global_store_short_d16_hi v153, v145, s[82:83] offset:64
	v_add_u32_e32 v154, 0x6ae00, v229
	v_add_u32_e32 v155, 0x6bd00, v229
	v_cvt_pk_bf16_f32 v146, v106, v107
	global_store_short v154, v146, s[82:83]
	global_store_short_d16_hi v155, v146, s[82:83]
	v_cvt_pk_bf16_f32 v147, v122, v123
	global_store_short v154, v147, s[82:83] offset:64
	global_store_short_d16_hi v155, v147, s[82:83] offset:64
	v_add_u32_e32 v156, 0x70800, v229
	v_add_u32_e32 v157, 0x71700, v229
	v_cvt_pk_bf16_f32 v148, v108, v109
	global_store_short v156, v148, s[82:83]
	global_store_short_d16_hi v157, v148, s[82:83]
	v_cvt_pk_bf16_f32 v149, v124, v125
	global_store_short v156, v149, s[82:83] offset:64
	global_store_short_d16_hi v157, v149, s[82:83] offset:64
	v_add_u32_e32 v158, 0x72600, v229
	v_add_u32_e32 v159, 0x73500, v229
	v_cvt_pk_bf16_f32 v150, v110, v111
	global_store_short v158, v150, s[82:83]
	global_store_short_d16_hi v159, v150, s[82:83]
	v_cvt_pk_bf16_f32 v151, v126, v127
	global_store_short v158, v151, s[82:83] offset:64
	global_store_short_d16_hi v159, v151, s[82:83] offset:64
	s_branch .Lmg_next
.Lmg_epi1:
	s_lshl_b32 s90, s78, 7
	s_add_u32 s90, s90, s67
	s_lshl_b32 s91, s79, 6
	s_add_u32 s91, s91, s68
	s_cmp_lt_u32 s67, 0x8000
	s_cbranch_scc1 .Lmg_rlat_13
	s_add_u32 s82, s24, 0x19d80000
	s_addc_u32 s83, s25, 0
	s_sub_u32 s0, s90, 0x8000
	s_mov_b32 s1, 8
	s_mov_b32 s10, 16
	s_branch .Lmg_rj_14
; #define RES_LD(X, mi_, ni_) { _Pragma("unroll") for (int r = 0; r < 16; ++r) X[r] = xo_base[(size_t)((mi_) * 32 + crow(r, h)) * D + (ni_) * 32]; }
; #define RES_ST(X, mi_, ni_) { _Pragma("unroll") for (int r = 0; r < 16; ++r) xn_base[(size_t)((mi_) * 32 + crow(r, h)) * D + (ni_) * 32] = X[r] + gate[ni_] * acc[mi_][ni_][r]; }
; template <int EPI>
; DI void epilogue(const Params& p, int layer, f32x16 (&acc)[2][2], int mrow0, int ncol0, int lane) {
;     ...
;   } else if (EPI == EPI_RES1 || EPI == EPI_RES2) {
;     const float* mod = (const float*)(p.ws + OFF_MOD) + (size_t)layer * 9 * 6144;
;     const int b9 = mrow0 < NLAT ? (mrow0 >> 12) : 8;
;     const int gsel = (EPI == EPI_RES1) ? 2 : 5;
;     const bool first = (EPI == EPI_RES1) && layer == 0;
;     const float* xo_base = xold_ptr(p, layer, first, mrow0) + (ncol0 + c);
;     float* xn_base = xnew_ptr(p, mrow0) + (ncol0 + c);
;     float gate[2];
; #pragma unroll
;     for (int ni = 0; ni < 2; ++ni) gate[ni] = mod[b9 * 6144 + gsel * 1024 + ncol0 + ni * 32 + c];
;     float xa[16], xb[16];
;     ...
;     RES_LD(xa, 0, 0)
;     RES_LD(xb, 0, 1)
;     RES_ST(xa, 0, 0)
;     RES_LD(xa, 1, 0)
;     RES_ST(xb, 0, 1)
;     RES_LD(xb, 1, 1)
;     RES_ST(xa, 1, 0)
;     RES_ST(xb, 1, 1)
.Lmg_rlat_13:
	s_mov_b32 s82, s22
	s_mov_b32 s83, s23
	s_mov_b32 s0, s90
	s_lshr_b32 s1, s67, 12
	s_mov_b32 s10, 0
.Lmg_rj_14:
	s_mov_b32 s84, s82
	s_mov_b32 s85, s83
	s_mov_b32 s11, 5
	s_cmp_eq_u32 s52, 1
	s_cbranch_scc0 .Lmg_rnf_15
	s_mov_b32 s11, 2
	s_cmp_eq_u32 s53, 0
	s_cbranch_scc0 .Lmg_rnf_15
	v_readlane_b32 s28, v255, 1
	v_readlane_b32 s29, v255, 2
	s_nop 4
	s_load_dwordx2 s[84:85], s[28:29], s10
	s_waitcnt lgkmcnt(0)
.Lmg_rnf_15:
	s_mul_i32 s12, s53, 9
	s_add_u32 s12, s12, s1
	s_mul_i32 s12, s12, 6144
	s_lshl_b32 s11, s11, 10
	s_add_u32 s12, s12, s11
	s_add_u32 s12, s12, s91
	s_lshl_b32 s12, s12, 2
	s_add_u32 s12, s12, 0x1d300000
	s_add_u32 s86, s24, s12
	s_addc_u32 s87, s25, 0
	v_lshlrev_b32_e32 v184, 2, v227
	global_load_dword v229, v184, s[86:87]
	global_load_dword v230, v184, s[86:87] offset:128
	v_lshl_add_u32 v185, v228, 2, s0
	v_lshlrev_b32_e32 v185, 10, v185
	v_add3_u32 v185, v185, s91, v227
	v_lshlrev_b32_e32 v231, 2, v185
	s_waitcnt lgkmcnt(0)
	v_mov_b32_e32 v144, v231
	v_add_u32_e32 v145, 0x1000, v231
	v_add_u32_e32 v146, 0x2000, v231
	v_add_u32_e32 v147, 0x3000, v231
	v_add_u32_e32 v148, 0x8000, v231
	v_add_u32_e32 v149, 0x9000, v231
	v_add_u32_e32 v150, 0xa000, v231
	v_add_u32_e32 v151, 0xb000, v231
	v_add_u32_e32 v152, 0x10000, v231
	v_add_u32_e32 v153, 0x11000, v231
	v_add_u32_e32 v154, 0x12000, v231
	v_add_u32_e32 v155, 0x13000, v231
	v_add_u32_e32 v156, 0x18000, v231
	v_add_u32_e32 v157, 0x19000, v231
	v_add_u32_e32 v158, 0x1a000, v231
	v_add_u32_e32 v159, 0x1b000, v231
	global_load_dword v237, v144, s[84:85]
	global_load_dword v238, v145, s[84:85]
	global_load_dword v239, v146, s[84:85]
	global_load_dword v240, v147, s[84:85]
	global_load_dword v241, v148, s[84:85]
	global_load_dword v242, v149, s[84:85]
	global_load_dword v243, v150, s[84:85]
	global_load_dword v244, v151, s[84:85]
	global_load_dword v245, v152, s[84:85]
	global_load_dword v246, v153, s[84:85]
	global_load_dword v247, v154, s[84:85]
	global_load_dword v248, v155, s[84:85]
	global_load_dword v249, v156, s[84:85]
	global_load_dword v250, v157, s[84:85]
	global_load_dword v251, v158, s[84:85]
	global_load_dword v252, v159, s[84:85]
	global_load_dword v176, v144, s[84:85] offset:128
	global_load_dword v177, v145, s[84:85] offset:128
	global_load_dword v178, v146, s[84:85] offset:128
	global_load_dword v179, v147, s[84:85] offset:128
	global_load_dword v180, v148, s[84:85] offset:128
	global_load_dword v181, v149, s[84:85] offset:128
	global_load_dword v182, v150, s[84:85] offset:128
	global_load_dword v183, v151, s[84:85] offset:128
	global_load_dword v184, v152, s[84:85] offset:128
	global_load_dword v185, v153, s[84:85] offset:128
	global_load_dword v186, v154, s[84:85] offset:128
	global_load_dword v187, v155, s[84:85] offset:128
	global_load_dword v128, v156, s[84:85] offset:128
	global_load_dword v129, v157, s[84:85] offset:128
	global_load_dword v130, v158, s[84:85] offset:128
	global_load_dword v131, v159, s[84:85] offset:128
	v_add_u32_e32 v160, 0x20000, v231
	v_add_u32_e32 v161, 0x21000, v231
	v_add_u32_e32 v162, 0x22000, v231
	v_add_u32_e32 v163, 0x23000, v231
	v_add_u32_e32 v164, 0x28000, v231
	v_add_u32_e32 v165, 0x29000, v231
	v_add_u32_e32 v166, 0x2a000, v231
	v_add_u32_e32 v167, 0x2b000, v231
	v_add_u32_e32 v168, 0x30000, v231
	v_add_u32_e32 v169, 0x31000, v231
	v_add_u32_e32 v170, 0x32000, v231
	v_add_u32_e32 v171, 0x33000, v231
	v_add_u32_e32 v172, 0x38000, v231
	v_add_u32_e32 v173, 0x39000, v231
	v_add_u32_e32 v174, 0x3a000, v231
	v_add_u32_e32 v175, 0x3b000, v231
	s_waitcnt vmcnt(16)
	v_fmac_f32_e32 v237, v229, v0
	v_fmac_f32_e32 v238, v229, v1
	v_fmac_f32_e32 v239, v229, v2
	v_fmac_f32_e32 v240, v229, v3
	v_fmac_f32_e32 v241, v229, v4
	v_fmac_f32_e32 v242, v229, v5
	v_fmac_f32_e32 v243, v229, v6
	v_fmac_f32_e32 v244, v229, v7
	v_fmac_f32_e32 v245, v229, v8
	v_fmac_f32_e32 v246, v229, v9
	v_fmac_f32_e32 v247, v229, v10
	v_fmac_f32_e32 v248, v229, v11
	v_fmac_f32_e32 v249, v229, v12
	v_fmac_f32_e32 v250, v229, v13
	v_fmac_f32_e32 v251, v229, v14
	v_fmac_f32_e32 v252, v229, v15
	global_store_dword v144, v237, s[82:83]
	global_store_dword v145, v238, s[82:83]
	global_store_dword v146, v239, s[82:83]
	global_store_dword v147, v240, s[82:83]
	global_store_dword v148, v241, s[82:83]
	global_store_dword v149, v242, s[82:83]
	global_store_dword v150, v243, s[82:83]
	global_store_dword v151, v244, s[82:83]
	global_store_dword v152, v245, s[82:83]
	global_store_dword v153, v246, s[82:83]
	global_store_dword v154, v247, s[82:83]
	global_store_dword v155, v248, s[82:83]
	global_store_dword v156, v249, s[82:83]
	global_store_dword v157, v250, s[82:83]
	global_store_dword v158, v251, s[82:83]
	global_store_dword v159, v252, s[82:83]
	global_load_dword v237, v160, s[84:85]
	global_load_dword v238, v161, s[84:85]
	global_load_dword v239, v162, s[84:85]
	global_load_dword v240, v163, s[84:85]
	global_load_dword v241, v164, s[84:85]
	global_load_dword v242, v165, s[84:85]
	global_load_dword v243, v166, s[84:85]
	global_load_dword v244, v167, s[84:85]
	global_load_dword v245, v168, s[84:85]
	global_load_dword v246, v169, s[84:85]
	global_load_dword v247, v170, s[84:85]
	global_load_dword v248, v171, s[84:85]
	global_load_dword v249, v172, s[84:85]
	global_load_dword v250, v173, s[84:85]
	global_load_dword v251, v174, s[84:85]
	global_load_dword v252, v175, s[84:85]
	s_waitcnt vmcnt(32)
; #define RES_LD(X, mi_, ni_) { _Pragma("unroll") for (int r = 0; r < 16; ++r) X[r] = xo_base[(size_t)((mi_) * 32 + crow(r, h)) * D + (ni_) * 32]; }
; #define RES_ST(X, mi_, ni_) { _Pragma("unroll") for (int r = 0; r < 16; ++r) xn_base[(size_t)((mi_) * 32 + crow(r, h)) * D + (ni_) * 32] = X[r] + gate[ni_] * acc[mi_][ni_][r]; }
; template <int EPI>
; DI void epilogue(const Params& p, int layer, f32x16 (&acc)[2][2], int mrow0, int ncol0, int lane) {
;     ...
;     RES_LD(xa, 0, 0)
;     RES_LD(xb, 0, 1)
;     RES_ST(xa, 0, 0)
;     RES_LD(xa, 1, 0)
;     RES_ST(xb, 0, 1)
;     RES_LD(xb, 1, 1)
;     RES_ST(xa, 1, 0)
;     RES_ST(xb, 1, 1)
	v_fmac_f32_e32 v176, v230, v16
	v_fmac_f32_e32 v177, v230, v17
	v_fmac_f32_e32 v178, v230, v18
	v_fmac_f32_e32 v179, v230, v19
	v_fmac_f32_e32 v180, v230, v20
	v_fmac_f32_e32 v181, v230, v21
	v_fmac_f32_e32 v182, v230, v22
	v_fmac_f32_e32 v183, v230, v23
	v_fmac_f32_e32 v184, v230, v24
	v_fmac_f32_e32 v185, v230, v25
	v_fmac_f32_e32 v186, v230, v26
	v_fmac_f32_e32 v187, v230, v27
	v_fmac_f32_e32 v128, v230, v28
	v_fmac_f32_e32 v129, v230, v29
	v_fmac_f32_e32 v130, v230, v30
	v_fmac_f32_e32 v131, v230, v31
	global_store_dword v144, v176, s[82:83] offset:128
	global_store_dword v145, v177, s[82:83] offset:128
	global_store_dword v146, v178, s[82:83] offset:128
	global_store_dword v147, v179, s[82:83] offset:128
	global_store_dword v148, v180, s[82:83] offset:128
	global_store_dword v149, v181, s[82:83] offset:128
	global_store_dword v150, v182, s[82:83] offset:128
	global_store_dword v151, v183, s[82:83] offset:128
	global_store_dword v152, v184, s[82:83] offset:128
	global_store_dword v153, v185, s[82:83] offset:128
	global_store_dword v154, v186, s[82:83] offset:128
	global_store_dword v155, v187, s[82:83] offset:128
	global_store_dword v156, v128, s[82:83] offset:128
	global_store_dword v157, v129, s[82:83] offset:128
	global_store_dword v158, v130, s[82:83] offset:128
	global_store_dword v159, v131, s[82:83] offset:128
	global_load_dword v176, v160, s[84:85] offset:128
	global_load_dword v177, v161, s[84:85] offset:128
	global_load_dword v178, v162, s[84:85] offset:128
	global_load_dword v179, v163, s[84:85] offset:128
	global_load_dword v180, v164, s[84:85] offset:128
	global_load_dword v181, v165, s[84:85] offset:128
	global_load_dword v182, v166, s[84:85] offset:128
	global_load_dword v183, v167, s[84:85] offset:128
	global_load_dword v184, v168, s[84:85] offset:128
	global_load_dword v185, v169, s[84:85] offset:128
	global_load_dword v186, v170, s[84:85] offset:128
	global_load_dword v187, v171, s[84:85] offset:128
	global_load_dword v128, v172, s[84:85] offset:128
	global_load_dword v129, v173, s[84:85] offset:128
	global_load_dword v130, v174, s[84:85] offset:128
	global_load_dword v131, v175, s[84:85] offset:128
	v_add_u32_e32 v144, 0x40000, v231
	v_add_u32_e32 v145, 0x41000, v231
	v_add_u32_e32 v146, 0x42000, v231
	v_add_u32_e32 v147, 0x43000, v231
	v_add_u32_e32 v148, 0x48000, v231
	v_add_u32_e32 v149, 0x49000, v231
	v_add_u32_e32 v150, 0x4a000, v231
	v_add_u32_e32 v151, 0x4b000, v231
	v_add_u32_e32 v152, 0x50000, v231
	v_add_u32_e32 v153, 0x51000, v231
	v_add_u32_e32 v154, 0x52000, v231
	v_add_u32_e32 v155, 0x53000, v231
	v_add_u32_e32 v156, 0x58000, v231
	v_add_u32_e32 v157, 0x59000, v231
	v_add_u32_e32 v158, 0x5a000, v231
	v_add_u32_e32 v159, 0x5b000, v231
	s_waitcnt vmcnt(32)
	v_fmac_f32_e32 v237, v229, v32
	v_fmac_f32_e32 v238, v229, v33
	v_fmac_f32_e32 v239, v229, v34
	v_fmac_f32_e32 v240, v229, v35
	v_fmac_f32_e32 v241, v229, v36
	v_fmac_f32_e32 v242, v229, v37
	v_fmac_f32_e32 v243, v229, v38
	v_fmac_f32_e32 v244, v229, v39
	v_fmac_f32_e32 v245, v229, v40
	v_fmac_f32_e32 v246, v229, v41
	v_fmac_f32_e32 v247, v229, v42
	v_fmac_f32_e32 v248, v229, v43
	v_fmac_f32_e32 v249, v229, v44
	v_fmac_f32_e32 v250, v229, v45
	v_fmac_f32_e32 v251, v229, v46
	v_fmac_f32_e32 v252, v229, v47
	global_store_dword v160, v237, s[82:83]
	global_store_dword v161, v238, s[82:83]
	global_store_dword v162, v239, s[82:83]
	global_store_dword v163, v240, s[82:83]
	global_store_dword v164, v241, s[82:83]
	global_store_dword v165, v242, s[82:83]
	global_store_dword v166, v243, s[82:83]
	global_store_dword v167, v244, s[82:83]
	global_store_dword v168, v245, s[82:83]
	global_store_dword v169, v246, s[82:83]
	global_store_dword v170, v247, s[82:83]
	global_store_dword v171, v248, s[82:83]
	global_store_dword v172, v249, s[82:83]
	global_store_dword v173, v250, s[82:83]
	global_store_dword v174, v251, s[82:83]
	global_store_dword v175, v252, s[82:83]
	global_load_dword v237, v144, s[84:85]
	global_load_dword v238, v145, s[84:85]
	global_load_dword v239, v146, s[84:85]
	global_load_dword v240, v147, s[84:85]
	global_load_dword v241, v148, s[84:85]
	global_load_dword v242, v149, s[84:85]
	global_load_dword v243, v150, s[84:85]
	global_load_dword v244, v151, s[84:85]
	global_load_dword v245, v152, s[84:85]
	global_load_dword v246, v153, s[84:85]
	global_load_dword v247, v154, s[84:85]
	global_load_dword v248, v155, s[84:85]
	global_load_dword v249, v156, s[84:85]
	global_load_dword v250, v157, s[84:85]
	global_load_dword v251, v158, s[84:85]
	global_load_dword v252, v159, s[84:85]
	s_waitcnt vmcnt(32)
; #define RES_LD(X, mi_, ni_) { _Pragma("unroll") for (int r = 0; r < 16; ++r) X[r] = xo_base[(size_t)((mi_) * 32 + crow(r, h)) * D + (ni_) * 32]; }
; #define RES_ST(X, mi_, ni_) { _Pragma("unroll") for (int r = 0; r < 16; ++r) xn_base[(size_t)((mi_) * 32 + crow(r, h)) * D + (ni_) * 32] = X[r] + gate[ni_] * acc[mi_][ni_][r]; }
; template <int EPI>
; DI void epilogue(const Params& p, int layer, f32x16 (&acc)[2][2], int mrow0, int ncol0, int lane) {
;     ...
;     RES_LD(xa, 0, 0)
;     RES_LD(xb, 0, 1)
;     RES_ST(xa, 0, 0)
;     RES_LD(xa, 1, 0)
;     RES_ST(xb, 0, 1)
;     RES_LD(xb, 1, 1)
;     RES_ST(xa, 1, 0)
;     RES_ST(xb, 1, 1)
	v_fmac_f32_e32 v176, v230, v48
	v_fmac_f32_e32 v177, v230, v49
	v_fmac_f32_e32 v178, v230, v50
	v_fmac_f32_e32 v179, v230, v51
	v_fmac_f32_e32 v180, v230, v52
	v_fmac_f32_e32 v181, v230, v53
	v_fmac_f32_e32 v182, v230, v54
	v_fmac_f32_e32 v183, v230, v55
	v_fmac_f32_e32 v184, v230, v56
	v_fmac_f32_e32 v185, v230, v57
	v_fmac_f32_e32 v186, v230, v58
	v_fmac_f32_e32 v187, v230, v59
	v_fmac_f32_e32 v128, v230, v60
	v_fmac_f32_e32 v129, v230, v61
	v_fmac_f32_e32 v130, v230, v62
	v_fmac_f32_e32 v131, v230, v63
	global_store_dword v160, v176, s[82:83] offset:128
	global_store_dword v161, v177, s[82:83] offset:128
	global_store_dword v162, v178, s[82:83] offset:128
	global_store_dword v163, v179, s[82:83] offset:128
	global_store_dword v164, v180, s[82:83] offset:128
	global_store_dword v165, v181, s[82:83] offset:128
	global_store_dword v166, v182, s[82:83] offset:128
	global_store_dword v167, v183, s[82:83] offset:128
	global_store_dword v168, v184, s[82:83] offset:128
	global_store_dword v169, v185, s[82:83] offset:128
	global_store_dword v170, v186, s[82:83] offset:128
	global_store_dword v171, v187, s[82:83] offset:128
	global_store_dword v172, v128, s[82:83] offset:128
	global_store_dword v173, v129, s[82:83] offset:128
	global_store_dword v174, v130, s[82:83] offset:128
	global_store_dword v175, v131, s[82:83] offset:128
	global_load_dword v176, v144, s[84:85] offset:128
	global_load_dword v177, v145, s[84:85] offset:128
	global_load_dword v178, v146, s[84:85] offset:128
	global_load_dword v179, v147, s[84:85] offset:128
	global_load_dword v180, v148, s[84:85] offset:128
	global_load_dword v181, v149, s[84:85] offset:128
	global_load_dword v182, v150, s[84:85] offset:128
	global_load_dword v183, v151, s[84:85] offset:128
	global_load_dword v184, v152, s[84:85] offset:128
	global_load_dword v185, v153, s[84:85] offset:128
	global_load_dword v186, v154, s[84:85] offset:128
	global_load_dword v187, v155, s[84:85] offset:128
	global_load_dword v128, v156, s[84:85] offset:128
	global_load_dword v129, v157, s[84:85] offset:128
	global_load_dword v130, v158, s[84:85] offset:128
	global_load_dword v131, v159, s[84:85] offset:128
	v_add_u32_e32 v160, 0x60000, v231
	v_add_u32_e32 v161, 0x61000, v231
	v_add_u32_e32 v162, 0x62000, v231
	v_add_u32_e32 v163, 0x63000, v231
	v_add_u32_e32 v164, 0x68000, v231
	v_add_u32_e32 v165, 0x69000, v231
	v_add_u32_e32 v166, 0x6a000, v231
	v_add_u32_e32 v167, 0x6b000, v231
	v_add_u32_e32 v168, 0x70000, v231
	v_add_u32_e32 v169, 0x71000, v231
	v_add_u32_e32 v170, 0x72000, v231
	v_add_u32_e32 v171, 0x73000, v231
	v_add_u32_e32 v172, 0x78000, v231
	v_add_u32_e32 v173, 0x79000, v231
	v_add_u32_e32 v174, 0x7a000, v231
	v_add_u32_e32 v175, 0x7b000, v231
	s_waitcnt vmcnt(32)
	v_fmac_f32_e32 v237, v229, v64
	v_fmac_f32_e32 v238, v229, v65
	v_fmac_f32_e32 v239, v229, v66
	v_fmac_f32_e32 v240, v229, v67
	v_fmac_f32_e32 v241, v229, v68
	v_fmac_f32_e32 v242, v229, v69
	v_fmac_f32_e32 v243, v229, v70
	v_fmac_f32_e32 v244, v229, v71
	v_fmac_f32_e32 v245, v229, v72
	v_fmac_f32_e32 v246, v229, v73
	v_fmac_f32_e32 v247, v229, v74
	v_fmac_f32_e32 v248, v229, v75
	v_fmac_f32_e32 v249, v229, v76
	v_fmac_f32_e32 v250, v229, v77
	v_fmac_f32_e32 v251, v229, v78
	v_fmac_f32_e32 v252, v229, v79
	global_store_dword v144, v237, s[82:83]
	global_store_dword v145, v238, s[82:83]
	global_store_dword v146, v239, s[82:83]
	global_store_dword v147, v240, s[82:83]
	global_store_dword v148, v241, s[82:83]
	global_store_dword v149, v242, s[82:83]
	global_store_dword v150, v243, s[82:83]
	global_store_dword v151, v244, s[82:83]
	global_store_dword v152, v245, s[82:83]
	global_store_dword v153, v246, s[82:83]
	global_store_dword v154, v247, s[82:83]
	global_store_dword v155, v248, s[82:83]
	global_store_dword v156, v249, s[82:83]
	global_store_dword v157, v250, s[82:83]
	global_store_dword v158, v251, s[82:83]
	global_store_dword v159, v252, s[82:83]
	global_load_dword v237, v160, s[84:85]
	global_load_dword v238, v161, s[84:85]
	global_load_dword v239, v162, s[84:85]
	global_load_dword v240, v163, s[84:85]
	global_load_dword v241, v164, s[84:85]
	global_load_dword v242, v165, s[84:85]
	global_load_dword v243, v166, s[84:85]
	global_load_dword v244, v167, s[84:85]
	global_load_dword v245, v168, s[84:85]
	global_load_dword v246, v169, s[84:85]
	global_load_dword v247, v170, s[84:85]
	global_load_dword v248, v171, s[84:85]
	global_load_dword v249, v172, s[84:85]
	global_load_dword v250, v173, s[84:85]
	global_load_dword v251, v174, s[84:85]
	global_load_dword v252, v175, s[84:85]
	s_waitcnt vmcnt(32)
; #define RES_LD(X, mi_, ni_) { _Pragma("unroll") for (int r = 0; r < 16; ++r) X[r] = xo_base[(size_t)((mi_) * 32 + crow(r, h)) * D + (ni_) * 32]; }
; #define RES_ST(X, mi_, ni_) { _Pragma("unroll") for (int r = 0; r < 16; ++r) xn_base[(size_t)((mi_) * 32 + crow(r, h)) * D + (ni_) * 32] = X[r] + gate[ni_] * acc[mi_][ni_][r]; }
; template <int EPI>
; DI void epilogue(const Params& p, int layer, f32x16 (&acc)[2][2], int mrow0, int ncol0, int lane) {
;     ...
;     RES_LD(xa, 0, 0)
;     RES_LD(xb, 0, 1)
;     RES_ST(xa, 0, 0)
;     RES_LD(xa, 1, 0)
;     RES_ST(xb, 0, 1)
;     RES_LD(xb, 1, 1)
;     RES_ST(xa, 1, 0)
;     RES_ST(xb, 1, 1)
	v_fmac_f32_e32 v176, v230, v80
	v_fmac_f32_e32 v177, v230, v81
	v_fmac_f32_e32 v178, v230, v82
	v_fmac_f32_e32 v179, v230, v83
	v_fmac_f32_e32 v180, v230, v84
	v_fmac_f32_e32 v181, v230, v85
	v_fmac_f32_e32 v182, v230, v86
	v_fmac_f32_e32 v183, v230, v87
	v_fmac_f32_e32 v184, v230, v88
	v_fmac_f32_e32 v185, v230, v89
	v_fmac_f32_e32 v186, v230, v90
	v_fmac_f32_e32 v187, v230, v91
	v_fmac_f32_e32 v128, v230, v92
	v_fmac_f32_e32 v129, v230, v93
	v_fmac_f32_e32 v130, v230, v94
	v_fmac_f32_e32 v131, v230, v95
	global_store_dword v144, v176, s[82:83] offset:128
	global_store_dword v145, v177, s[82:83] offset:128
	global_store_dword v146, v178, s[82:83] offset:128
	global_store_dword v147, v179, s[82:83] offset:128
	global_store_dword v148, v180, s[82:83] offset:128
	global_store_dword v149, v181, s[82:83] offset:128
	global_store_dword v150, v182, s[82:83] offset:128
	global_store_dword v151, v183, s[82:83] offset:128
	global_store_dword v152, v184, s[82:83] offset:128
	global_store_dword v153, v185, s[82:83] offset:128
	global_store_dword v154, v186, s[82:83] offset:128
	global_store_dword v155, v187, s[82:83] offset:128
	global_store_dword v156, v128, s[82:83] offset:128
	global_store_dword v157, v129, s[82:83] offset:128
	global_store_dword v158, v130, s[82:83] offset:128
	global_store_dword v159, v131, s[82:83] offset:128
	global_load_dword v176, v160, s[84:85] offset:128
	global_load_dword v177, v161, s[84:85] offset:128
	global_load_dword v178, v162, s[84:85] offset:128
	global_load_dword v179, v163, s[84:85] offset:128
	global_load_dword v180, v164, s[84:85] offset:128
	global_load_dword v181, v165, s[84:85] offset:128
	global_load_dword v182, v166, s[84:85] offset:128
	global_load_dword v183, v167, s[84:85] offset:128
	global_load_dword v184, v168, s[84:85] offset:128
	global_load_dword v185, v169, s[84:85] offset:128
	global_load_dword v186, v170, s[84:85] offset:128
	global_load_dword v187, v171, s[84:85] offset:128
	global_load_dword v128, v172, s[84:85] offset:128
	global_load_dword v129, v173, s[84:85] offset:128
	global_load_dword v130, v174, s[84:85] offset:128
	global_load_dword v131, v175, s[84:85] offset:128
	s_waitcnt vmcnt(32)
	v_fmac_f32_e32 v237, v229, v96
	v_fmac_f32_e32 v238, v229, v97
	v_fmac_f32_e32 v239, v229, v98
	v_fmac_f32_e32 v240, v229, v99
	v_fmac_f32_e32 v241, v229, v100
	v_fmac_f32_e32 v242, v229, v101
	v_fmac_f32_e32 v243, v229, v102
	v_fmac_f32_e32 v244, v229, v103
	v_fmac_f32_e32 v245, v229, v104
	v_fmac_f32_e32 v246, v229, v105
	v_fmac_f32_e32 v247, v229, v106
	v_fmac_f32_e32 v248, v229, v107
	v_fmac_f32_e32 v249, v229, v108
	v_fmac_f32_e32 v250, v229, v109
	v_fmac_f32_e32 v251, v229, v110
	v_fmac_f32_e32 v252, v229, v111
	global_store_dword v160, v237, s[82:83]
	global_store_dword v161, v238, s[82:83]
	global_store_dword v162, v239, s[82:83]
	global_store_dword v163, v240, s[82:83]
	global_store_dword v164, v241, s[82:83]
	global_store_dword v165, v242, s[82:83]
	global_store_dword v166, v243, s[82:83]
	global_store_dword v167, v244, s[82:83]
	global_store_dword v168, v245, s[82:83]
	global_store_dword v169, v246, s[82:83]
	global_store_dword v170, v247, s[82:83]
	global_store_dword v171, v248, s[82:83]
	global_store_dword v172, v249, s[82:83]
	global_store_dword v173, v250, s[82:83]
	global_store_dword v174, v251, s[82:83]
	global_store_dword v175, v252, s[82:83]
	s_waitcnt vmcnt(16)
	v_fmac_f32_e32 v176, v230, v112
	v_fmac_f32_e32 v177, v230, v113
	v_fmac_f32_e32 v178, v230, v114
	v_fmac_f32_e32 v179, v230, v115
	v_fmac_f32_e32 v180, v230, v116
	v_fmac_f32_e32 v181, v230, v117
	v_fmac_f32_e32 v182, v230, v118
	v_fmac_f32_e32 v183, v230, v119
	v_fmac_f32_e32 v184, v230, v120
	v_fmac_f32_e32 v185, v230, v121
	v_fmac_f32_e32 v186, v230, v122
	v_fmac_f32_e32 v187, v230, v123
	v_fmac_f32_e32 v128, v230, v124
	v_fmac_f32_e32 v129, v230, v125
	v_fmac_f32_e32 v130, v230, v126
	v_fmac_f32_e32 v131, v230, v127
	global_store_dword v160, v176, s[82:83] offset:128
	global_store_dword v161, v177, s[82:83] offset:128
	global_store_dword v162, v178, s[82:83] offset:128
	global_store_dword v163, v179, s[82:83] offset:128
	global_store_dword v164, v180, s[82:83] offset:128
	global_store_dword v165, v181, s[82:83] offset:128
	global_store_dword v166, v182, s[82:83] offset:128
	global_store_dword v167, v183, s[82:83] offset:128
	global_store_dword v168, v184, s[82:83] offset:128
	global_store_dword v169, v185, s[82:83] offset:128
	global_store_dword v170, v186, s[82:83] offset:128
	global_store_dword v171, v187, s[82:83] offset:128
	global_store_dword v172, v128, s[82:83] offset:128
	global_store_dword v173, v129, s[82:83] offset:128
	global_store_dword v174, v130, s[82:83] offset:128
	global_store_dword v175, v131, s[82:83] offset:128
	s_branch .Lmg_next

; DI bf16_t f2bf(float x) { return (bf16_t)(pack2(x, x) & 0xffffu); }
; DI int crow(int reg, int h) { return (reg & 3) + 8 * (reg >> 2) + 4 * h; }
; DI float silu_f(float x) { return x * __builtin_amdgcn_rcpf(1.0f + __expf(-x)); }
; template <int EPI>
; DI void epilogue(const Params& p, int layer, f32x16 (&acc)[2][2], int mrow0, int ncol0, int lane) {
;     ...
;   } else if (EPI == EPI_SWIGLU) {
;     bf16_t* G = (bf16_t*)(p.ws + OFF_U);
;     const int j = (ncol0 >> 7) * 64 + ((ncol0 >> 6) & 1) * 32 + c;
; #pragma unroll
;     for (int mi = 0; mi < 2; ++mi)
; #pragma unroll
;       for (int r = 0; r < 16; ++r) {
;         int row = mrow0 + mi * 32 + crow(r, h);
;         float a1 = acc[mi][0][r], a3 = acc[mi][1][r];
;         G[(size_t)row * FFH + j] = f2bf(silu_f(a1) * a3);
;       }
.Lmg_epi2:
	s_lshl_b32 s90, s78, 7
	s_add_u32 s90, s90, s67
	s_lshl_b32 s91, s79, 6
	s_add_u32 s91, s91, s68
	v_lshl_add_u32 v184, v228, 2, s90
	s_movk_i32 s0, 5632
	v_mul_lo_u32 v184, v184, s0
	s_lshr_b32 s1, s68, 7
	s_lshl_b32 s1, s1, 6
	s_lshl_b32 s10, s79, 5
	s_add_u32 s1, s1, s10
	v_add_u32_e32 v185, s1, v227
	v_lshl_add_u32 v229, v185, 1, v184
	s_mov_b32 s82, s24
	s_mov_b32 s83, s25
	v_mul_f32_e32 v144, 0xbfb8aa3b, v0
	v_mul_f32_e32 v145, 0xbfb8aa3b, v1
	v_mul_f32_e32 v146, 0xbfb8aa3b, v2
	v_mul_f32_e32 v147, 0xbfb8aa3b, v3
	v_exp_f32_e32 v144, v144
	v_exp_f32_e32 v145, v145
	v_exp_f32_e32 v146, v146
	v_exp_f32_e32 v147, v147
	v_mov_b32_e32 v148, v229
	v_add_u32_e32 v149, 0x1600, v229
	v_add_u32_e32 v150, 0x2c00, v229
	v_add_u32_e32 v151, 0x4200, v229
	v_add_f32_e32 v144, 1.0, v144
	v_add_f32_e32 v145, 1.0, v145
	v_add_f32_e32 v146, 1.0, v146
	v_add_f32_e32 v147, 1.0, v147
	v_rcp_f32_e32 v144, v144
	v_rcp_f32_e32 v145, v145
	v_rcp_f32_e32 v146, v146
	v_rcp_f32_e32 v147, v147
	s_nop 0
	v_mul_f32_e32 v144, v0, v144
	v_mul_f32_e32 v145, v1, v145
	v_mul_f32_e32 v146, v2, v146
	v_mul_f32_e32 v147, v3, v147
	v_mul_f32_e32 v144, v16, v144
	v_mul_f32_e32 v145, v17, v145
	v_mul_f32_e32 v146, v18, v146
	v_mul_f32_e32 v147, v19, v147
	v_cvt_pk_bf16_f32 v152, v144, v145
	v_cvt_pk_bf16_f32 v153, v146, v147
	global_store_short v148, v152, s[82:83]
	global_store_short_d16_hi v149, v152, s[82:83]
	global_store_short v150, v153, s[82:83]
	global_store_short_d16_hi v151, v153, s[82:83]
	v_mul_f32_e32 v144, 0xbfb8aa3b, v4
	v_mul_f32_e32 v145, 0xbfb8aa3b, v5
	v_mul_f32_e32 v146, 0xbfb8aa3b, v6
	v_mul_f32_e32 v147, 0xbfb8aa3b, v7
	v_exp_f32_e32 v144, v144
	v_exp_f32_e32 v145, v145
	v_exp_f32_e32 v146, v146
	v_exp_f32_e32 v147, v147
	v_add_u32_e32 v148, 0xb000, v229
	v_add_u32_e32 v149, 0xc600, v229
	v_add_u32_e32 v150, 0xdc00, v229
	v_add_u32_e32 v151, 0xf200, v229
	v_add_f32_e32 v144, 1.0, v144
	v_add_f32_e32 v145, 1.0, v145
	v_add_f32_e32 v146, 1.0, v146
	v_add_f32_e32 v147, 1.0, v147
	v_rcp_f32_e32 v144, v144
	v_rcp_f32_e32 v145, v145
	v_rcp_f32_e32 v146, v146
	v_rcp_f32_e32 v147, v147
	s_nop 0
	v_mul_f32_e32 v144, v4, v144
	v_mul_f32_e32 v145, v5, v145
	v_mul_f32_e32 v146, v6, v146
	v_mul_f32_e32 v147, v7, v147
	v_mul_f32_e32 v144, v20, v144
	v_mul_f32_e32 v145, v21, v145
	v_mul_f32_e32 v146, v22, v146
	v_mul_f32_e32 v147, v23, v147
	v_cvt_pk_bf16_f32 v154, v144, v145
	v_cvt_pk_bf16_f32 v155, v146, v147
	global_store_short v148, v154, s[82:83]
	global_store_short_d16_hi v149, v154, s[82:83]
	global_store_short v150, v155, s[82:83]
	global_store_short_d16_hi v151, v155, s[82:83]
	v_mul_f32_e32 v144, 0xbfb8aa3b, v8
	v_mul_f32_e32 v145, 0xbfb8aa3b, v9
	v_mul_f32_e32 v146, 0xbfb8aa3b, v10
	v_mul_f32_e32 v147, 0xbfb8aa3b, v11
	v_exp_f32_e32 v144, v144
	v_exp_f32_e32 v145, v145
	v_exp_f32_e32 v146, v146
	v_exp_f32_e32 v147, v147
	v_add_u32_e32 v148, 0x16000, v229
	v_add_u32_e32 v149, 0x17600, v229
	v_add_u32_e32 v150, 0x18c00, v229
	v_add_u32_e32 v151, 0x1a200, v229
	v_add_f32_e32 v144, 1.0, v144
	v_add_f32_e32 v145, 1.0, v145
	v_add_f32_e32 v146, 1.0, v146
	v_add_f32_e32 v147, 1.0, v147
	v_rcp_f32_e32 v144, v144
	v_rcp_f32_e32 v145, v145
	v_rcp_f32_e32 v146, v146
	v_rcp_f32_e32 v147, v147
	s_nop 0
	v_mul_f32_e32 v144, v8, v144
	v_mul_f32_e32 v145, v9, v145
	v_mul_f32_e32 v146, v10, v146
	v_mul_f32_e32 v147, v11, v147
	v_mul_f32_e32 v144, v24, v144
	v_mul_f32_e32 v145, v25, v145
	v_mul_f32_e32 v146, v26, v146
	v_mul_f32_e32 v147, v27, v147
	v_cvt_pk_bf16_f32 v152, v144, v145
	v_cvt_pk_bf16_f32 v153, v146, v147
	global_store_short v148, v152, s[82:83]
	global_store_short_d16_hi v149, v152, s[82:83]
	global_store_short v150, v153, s[82:83]
	global_store_short_d16_hi v151, v153, s[82:83]
	v_mul_f32_e32 v144, 0xbfb8aa3b, v12
	v_mul_f32_e32 v145, 0xbfb8aa3b, v13
	v_mul_f32_e32 v146, 0xbfb8aa3b, v14
	v_mul_f32_e32 v147, 0xbfb8aa3b, v15
	v_exp_f32_e32 v144, v144
	v_exp_f32_e32 v145, v145
	v_exp_f32_e32 v146, v146
	v_exp_f32_e32 v147, v147
	v_add_u32_e32 v148, 0x21000, v229
	v_add_u32_e32 v149, 0x22600, v229
	v_add_u32_e32 v150, 0x23c00, v229
	v_add_u32_e32 v151, 0x25200, v229
	v_add_f32_e32 v144, 1.0, v144
	v_add_f32_e32 v145, 1.0, v145
	v_add_f32_e32 v146, 1.0, v146
	v_add_f32_e32 v147, 1.0, v147
	v_rcp_f32_e32 v144, v144
	v_rcp_f32_e32 v145, v145
	v_rcp_f32_e32 v146, v146
	v_rcp_f32_e32 v147, v147
	s_nop 0
	v_mul_f32_e32 v144, v12, v144
	v_mul_f32_e32 v145, v13, v145
	v_mul_f32_e32 v146, v14, v146
	v_mul_f32_e32 v147, v15, v147
	v_mul_f32_e32 v144, v28, v144
	v_mul_f32_e32 v145, v29, v145
	v_mul_f32_e32 v146, v30, v146
	v_mul_f32_e32 v147, v31, v147
	v_cvt_pk_bf16_f32 v154, v144, v145
	v_cvt_pk_bf16_f32 v155, v146, v147
	global_store_short v148, v154, s[82:83]
	global_store_short_d16_hi v149, v154, s[82:83]
	global_store_short v150, v155, s[82:83]
	global_store_short_d16_hi v151, v155, s[82:83]
	v_mul_f32_e32 v144, 0xbfb8aa3b, v32
	v_mul_f32_e32 v145, 0xbfb8aa3b, v33
	v_mul_f32_e32 v146, 0xbfb8aa3b, v34
	v_mul_f32_e32 v147, 0xbfb8aa3b, v35
	v_exp_f32_e32 v144, v144
	v_exp_f32_e32 v145, v145
	v_exp_f32_e32 v146, v146
	v_exp_f32_e32 v147, v147
	v_add_u32_e32 v148, 0x2c000, v229
	v_add_u32_e32 v149, 0x2d600, v229
	v_add_u32_e32 v150, 0x2ec00, v229
	v_add_u32_e32 v151, 0x30200, v229
	v_add_f32_e32 v144, 1.0, v144
	v_add_f32_e32 v145, 1.0, v145
	v_add_f32_e32 v146, 1.0, v146
	v_add_f32_e32 v147, 1.0, v147
	v_rcp_f32_e32 v144, v144
	v_rcp_f32_e32 v145, v145
	v_rcp_f32_e32 v146, v146
	v_rcp_f32_e32 v147, v147
	s_nop 0
	v_mul_f32_e32 v144, v32, v144
	v_mul_f32_e32 v145, v33, v145
	v_mul_f32_e32 v146, v34, v146
	v_mul_f32_e32 v147, v35, v147
	v_mul_f32_e32 v144, v48, v144
; DI bf16_t f2bf(float x) { return (bf16_t)(pack2(x, x) & 0xffffu); }
; DI int crow(int reg, int h) { return (reg & 3) + 8 * (reg >> 2) + 4 * h; }
; DI float silu_f(float x) { return x * __builtin_amdgcn_rcpf(1.0f + __expf(-x)); }
; template <int EPI>
; DI void epilogue(const Params& p, int layer, f32x16 (&acc)[2][2], int mrow0, int ncol0, int lane) {
;     ...
;   } else if (EPI == EPI_SWIGLU) {
;     bf16_t* G = (bf16_t*)(p.ws + OFF_U);
;     const int j = (ncol0 >> 7) * 64 + ((ncol0 >> 6) & 1) * 32 + c;
; #pragma unroll
;     for (int mi = 0; mi < 2; ++mi)
; #pragma unroll
;       for (int r = 0; r < 16; ++r) {
;         int row = mrow0 + mi * 32 + crow(r, h);
;         float a1 = acc[mi][0][r], a3 = acc[mi][1][r];
;         G[(size_t)row * FFH + j] = f2bf(silu_f(a1) * a3);
;       }
	v_mul_f32_e32 v145, v49, v145
	v_mul_f32_e32 v146, v50, v146
	v_mul_f32_e32 v147, v51, v147
	v_cvt_pk_bf16_f32 v152, v144, v145
	v_cvt_pk_bf16_f32 v153, v146, v147
	global_store_short v148, v152, s[82:83]
	global_store_short_d16_hi v149, v152, s[82:83]
	global_store_short v150, v153, s[82:83]
	global_store_short_d16_hi v151, v153, s[82:83]
	v_mul_f32_e32 v144, 0xbfb8aa3b, v36
	v_mul_f32_e32 v145, 0xbfb8aa3b, v37
	v_mul_f32_e32 v146, 0xbfb8aa3b, v38
	v_mul_f32_e32 v147, 0xbfb8aa3b, v39
	v_exp_f32_e32 v144, v144
	v_exp_f32_e32 v145, v145
	v_exp_f32_e32 v146, v146
	v_exp_f32_e32 v147, v147
	v_add_u32_e32 v148, 0x37000, v229
	v_add_u32_e32 v149, 0x38600, v229
	v_add_u32_e32 v150, 0x39c00, v229
	v_add_u32_e32 v151, 0x3b200, v229
	v_add_f32_e32 v144, 1.0, v144
	v_add_f32_e32 v145, 1.0, v145
	v_add_f32_e32 v146, 1.0, v146
	v_add_f32_e32 v147, 1.0, v147
	v_rcp_f32_e32 v144, v144
	v_rcp_f32_e32 v145, v145
	v_rcp_f32_e32 v146, v146
	v_rcp_f32_e32 v147, v147
	s_nop 0
	v_mul_f32_e32 v144, v36, v144
	v_mul_f32_e32 v145, v37, v145
	v_mul_f32_e32 v146, v38, v146
	v_mul_f32_e32 v147, v39, v147
	v_mul_f32_e32 v144, v52, v144
	v_mul_f32_e32 v145, v53, v145
	v_mul_f32_e32 v146, v54, v146
	v_mul_f32_e32 v147, v55, v147
	v_cvt_pk_bf16_f32 v154, v144, v145
	v_cvt_pk_bf16_f32 v155, v146, v147
	global_store_short v148, v154, s[82:83]
	global_store_short_d16_hi v149, v154, s[82:83]
	global_store_short v150, v155, s[82:83]
	global_store_short_d16_hi v151, v155, s[82:83]
	v_mul_f32_e32 v144, 0xbfb8aa3b, v40
	v_mul_f32_e32 v145, 0xbfb8aa3b, v41
	v_mul_f32_e32 v146, 0xbfb8aa3b, v42
	v_mul_f32_e32 v147, 0xbfb8aa3b, v43
	v_exp_f32_e32 v144, v144
	v_exp_f32_e32 v145, v145
	v_exp_f32_e32 v146, v146
	v_exp_f32_e32 v147, v147
	v_add_u32_e32 v148, 0x42000, v229
	v_add_u32_e32 v149, 0x43600, v229
	v_add_u32_e32 v150, 0x44c00, v229
	v_add_u32_e32 v151, 0x46200, v229
	v_add_f32_e32 v144, 1.0, v144
	v_add_f32_e32 v145, 1.0, v145
	v_add_f32_e32 v146, 1.0, v146
	v_add_f32_e32 v147, 1.0, v147
	v_rcp_f32_e32 v144, v144
	v_rcp_f32_e32 v145, v145
	v_rcp_f32_e32 v146, v146
	v_rcp_f32_e32 v147, v147
	s_nop 0
	v_mul_f32_e32 v144, v40, v144
	v_mul_f32_e32 v145, v41, v145
	v_mul_f32_e32 v146, v42, v146
	v_mul_f32_e32 v147, v43, v147
	v_mul_f32_e32 v144, v56, v144
	v_mul_f32_e32 v145, v57, v145
	v_mul_f32_e32 v146, v58, v146
	v_mul_f32_e32 v147, v59, v147
	v_cvt_pk_bf16_f32 v152, v144, v145
	v_cvt_pk_bf16_f32 v153, v146, v147
	global_store_short v148, v152, s[82:83]
	global_store_short_d16_hi v149, v152, s[82:83]
	global_store_short v150, v153, s[82:83]
	global_store_short_d16_hi v151, v153, s[82:83]
	v_mul_f32_e32 v144, 0xbfb8aa3b, v44
	v_mul_f32_e32 v145, 0xbfb8aa3b, v45
	v_mul_f32_e32 v146, 0xbfb8aa3b, v46
	v_mul_f32_e32 v147, 0xbfb8aa3b, v47
	v_exp_f32_e32 v144, v144
	v_exp_f32_e32 v145, v145
	v_exp_f32_e32 v146, v146
	v_exp_f32_e32 v147, v147
	v_add_u32_e32 v148, 0x4d000, v229
	v_add_u32_e32 v149, 0x4e600, v229
	v_add_u32_e32 v150, 0x4fc00, v229
	v_add_u32_e32 v151, 0x51200, v229
	v_add_f32_e32 v144, 1.0, v144
	v_add_f32_e32 v145, 1.0, v145
	v_add_f32_e32 v146, 1.0, v146
	v_add_f32_e32 v147, 1.0, v147
	v_rcp_f32_e32 v144, v144
	v_rcp_f32_e32 v145, v145
	v_rcp_f32_e32 v146, v146
	v_rcp_f32_e32 v147, v147
	s_nop 0
	v_mul_f32_e32 v144, v44, v144
	v_mul_f32_e32 v145, v45, v145
	v_mul_f32_e32 v146, v46, v146
	v_mul_f32_e32 v147, v47, v147
	v_mul_f32_e32 v144, v60, v144
	v_mul_f32_e32 v145, v61, v145
	v_mul_f32_e32 v146, v62, v146
	v_mul_f32_e32 v147, v63, v147
	v_cvt_pk_bf16_f32 v154, v144, v145
	v_cvt_pk_bf16_f32 v155, v146, v147
	global_store_short v148, v154, s[82:83]
	global_store_short_d16_hi v149, v154, s[82:83]
	global_store_short v150, v155, s[82:83]
	global_store_short_d16_hi v151, v155, s[82:83]
	v_mul_f32_e32 v144, 0xbfb8aa3b, v64
	v_mul_f32_e32 v145, 0xbfb8aa3b, v65
	v_mul_f32_e32 v146, 0xbfb8aa3b, v66
	v_mul_f32_e32 v147, 0xbfb8aa3b, v67
	v_exp_f32_e32 v144, v144
	v_exp_f32_e32 v145, v145
	v_exp_f32_e32 v146, v146
	v_exp_f32_e32 v147, v147
	v_add_u32_e32 v148, 0x58000, v229
	v_add_u32_e32 v149, 0x59600, v229
	v_add_u32_e32 v150, 0x5ac00, v229
	v_add_u32_e32 v151, 0x5c200, v229
	v_add_f32_e32 v144, 1.0, v144
	v_add_f32_e32 v145, 1.0, v145
	v_add_f32_e32 v146, 1.0, v146
	v_add_f32_e32 v147, 1.0, v147
	v_rcp_f32_e32 v144, v144
	v_rcp_f32_e32 v145, v145
	v_rcp_f32_e32 v146, v146
	v_rcp_f32_e32 v147, v147
	s_nop 0
	v_mul_f32_e32 v144, v64, v144
	v_mul_f32_e32 v145, v65, v145
	v_mul_f32_e32 v146, v66, v146
	v_mul_f32_e32 v147, v67, v147
	v_mul_f32_e32 v144, v80, v144
	v_mul_f32_e32 v145, v81, v145
	v_mul_f32_e32 v146, v82, v146
	v_mul_f32_e32 v147, v83, v147
	v_cvt_pk_bf16_f32 v152, v144, v145
	v_cvt_pk_bf16_f32 v153, v146, v147
	global_store_short v148, v152, s[82:83]
	global_store_short_d16_hi v149, v152, s[82:83]
	global_store_short v150, v153, s[82:83]
	global_store_short_d16_hi v151, v153, s[82:83]
	v_mul_f32_e32 v144, 0xbfb8aa3b, v68
	v_mul_f32_e32 v145, 0xbfb8aa3b, v69
	v_mul_f32_e32 v146, 0xbfb8aa3b, v70
	v_mul_f32_e32 v147, 0xbfb8aa3b, v71
	v_exp_f32_e32 v144, v144
	v_exp_f32_e32 v145, v145
	v_exp_f32_e32 v146, v146
	v_exp_f32_e32 v147, v147
	v_add_u32_e32 v148, 0x63000, v229
	v_add_u32_e32 v149, 0x64600, v229
	v_add_u32_e32 v150, 0x65c00, v229
	v_add_u32_e32 v151, 0x67200, v229
	v_add_f32_e32 v144, 1.0, v144
	v_add_f32_e32 v145, 1.0, v145
	v_add_f32_e32 v146, 1.0, v146
	v_add_f32_e32 v147, 1.0, v147
	v_rcp_f32_e32 v144, v144
	v_rcp_f32_e32 v145, v145
	v_rcp_f32_e32 v146, v146
	v_rcp_f32_e32 v147, v147
	s_nop 0
	v_mul_f32_e32 v144, v68, v144
	v_mul_f32_e32 v145, v69, v145
	v_mul_f32_e32 v146, v70, v146
	v_mul_f32_e32 v147, v71, v147
	v_mul_f32_e32 v144, v84, v144
; DI bf16_t f2bf(float x) { return (bf16_t)(pack2(x, x) & 0xffffu); }
; DI int crow(int reg, int h) { return (reg & 3) + 8 * (reg >> 2) + 4 * h; }
; DI float silu_f(float x) { return x * __builtin_amdgcn_rcpf(1.0f + __expf(-x)); }
; template <int EPI>
; DI void epilogue(const Params& p, int layer, f32x16 (&acc)[2][2], int mrow0, int ncol0, int lane) {
;     ...
;   } else if (EPI == EPI_SWIGLU) {
;     bf16_t* G = (bf16_t*)(p.ws + OFF_U);
;     const int j = (ncol0 >> 7) * 64 + ((ncol0 >> 6) & 1) * 32 + c;
; #pragma unroll
;     for (int mi = 0; mi < 2; ++mi)
; #pragma unroll
;       for (int r = 0; r < 16; ++r) {
;         int row = mrow0 + mi * 32 + crow(r, h);
;         float a1 = acc[mi][0][r], a3 = acc[mi][1][r];
;         G[(size_t)row * FFH + j] = f2bf(silu_f(a1) * a3);
;       }
	v_mul_f32_e32 v145, v85, v145
	v_mul_f32_e32 v146, v86, v146
	v_mul_f32_e32 v147, v87, v147
	v_cvt_pk_bf16_f32 v154, v144, v145
	v_cvt_pk_bf16_f32 v155, v146, v147
	global_store_short v148, v154, s[82:83]
	global_store_short_d16_hi v149, v154, s[82:83]
	global_store_short v150, v155, s[82:83]
	global_store_short_d16_hi v151, v155, s[82:83]
	v_mul_f32_e32 v144, 0xbfb8aa3b, v72
	v_mul_f32_e32 v145, 0xbfb8aa3b, v73
	v_mul_f32_e32 v146, 0xbfb8aa3b, v74
	v_mul_f32_e32 v147, 0xbfb8aa3b, v75
	v_exp_f32_e32 v144, v144
	v_exp_f32_e32 v145, v145
	v_exp_f32_e32 v146, v146
	v_exp_f32_e32 v147, v147
	v_add_u32_e32 v148, 0x6e000, v229
	v_add_u32_e32 v149, 0x6f600, v229
	v_add_u32_e32 v150, 0x70c00, v229
	v_add_u32_e32 v151, 0x72200, v229
	v_add_f32_e32 v144, 1.0, v144
	v_add_f32_e32 v145, 1.0, v145
	v_add_f32_e32 v146, 1.0, v146
	v_add_f32_e32 v147, 1.0, v147
	v_rcp_f32_e32 v144, v144
	v_rcp_f32_e32 v145, v145
	v_rcp_f32_e32 v146, v146
	v_rcp_f32_e32 v147, v147
	s_nop 0
	v_mul_f32_e32 v144, v72, v144
	v_mul_f32_e32 v145, v73, v145
	v_mul_f32_e32 v146, v74, v146
	v_mul_f32_e32 v147, v75, v147
	v_mul_f32_e32 v144, v88, v144
	v_mul_f32_e32 v145, v89, v145
	v_mul_f32_e32 v146, v90, v146
	v_mul_f32_e32 v147, v91, v147
	v_cvt_pk_bf16_f32 v152, v144, v145
	v_cvt_pk_bf16_f32 v153, v146, v147
	global_store_short v148, v152, s[82:83]
	global_store_short_d16_hi v149, v152, s[82:83]
	global_store_short v150, v153, s[82:83]
	global_store_short_d16_hi v151, v153, s[82:83]
	v_mul_f32_e32 v144, 0xbfb8aa3b, v76
	v_mul_f32_e32 v145, 0xbfb8aa3b, v77
	v_mul_f32_e32 v146, 0xbfb8aa3b, v78
	v_mul_f32_e32 v147, 0xbfb8aa3b, v79
	v_exp_f32_e32 v144, v144
	v_exp_f32_e32 v145, v145
	v_exp_f32_e32 v146, v146
	v_exp_f32_e32 v147, v147
	v_add_u32_e32 v148, 0x79000, v229
	v_add_u32_e32 v149, 0x7a600, v229
	v_add_u32_e32 v150, 0x7bc00, v229
	v_add_u32_e32 v151, 0x7d200, v229
	v_add_f32_e32 v144, 1.0, v144
	v_add_f32_e32 v145, 1.0, v145
	v_add_f32_e32 v146, 1.0, v146
	v_add_f32_e32 v147, 1.0, v147
	v_rcp_f32_e32 v144, v144
	v_rcp_f32_e32 v145, v145
	v_rcp_f32_e32 v146, v146
	v_rcp_f32_e32 v147, v147
	s_nop 0
	v_mul_f32_e32 v144, v76, v144
	v_mul_f32_e32 v145, v77, v145
	v_mul_f32_e32 v146, v78, v146
	v_mul_f32_e32 v147, v79, v147
	v_mul_f32_e32 v144, v92, v144
	v_mul_f32_e32 v145, v93, v145
	v_mul_f32_e32 v146, v94, v146
	v_mul_f32_e32 v147, v95, v147
	v_cvt_pk_bf16_f32 v154, v144, v145
	v_cvt_pk_bf16_f32 v155, v146, v147
	global_store_short v148, v154, s[82:83]
	global_store_short_d16_hi v149, v154, s[82:83]
	global_store_short v150, v155, s[82:83]
	global_store_short_d16_hi v151, v155, s[82:83]
	v_mul_f32_e32 v144, 0xbfb8aa3b, v96
	v_mul_f32_e32 v145, 0xbfb8aa3b, v97
	v_mul_f32_e32 v146, 0xbfb8aa3b, v98
	v_mul_f32_e32 v147, 0xbfb8aa3b, v99
	v_exp_f32_e32 v144, v144
	v_exp_f32_e32 v145, v145
	v_exp_f32_e32 v146, v146
	v_exp_f32_e32 v147, v147
	v_add_u32_e32 v148, 0x84000, v229
	v_add_u32_e32 v149, 0x85600, v229
	v_add_u32_e32 v150, 0x86c00, v229
	v_add_u32_e32 v151, 0x88200, v229
	v_add_f32_e32 v144, 1.0, v144
	v_add_f32_e32 v145, 1.0, v145
	v_add_f32_e32 v146, 1.0, v146
	v_add_f32_e32 v147, 1.0, v147
	v_rcp_f32_e32 v144, v144
	v_rcp_f32_e32 v145, v145
	v_rcp_f32_e32 v146, v146
	v_rcp_f32_e32 v147, v147
	s_nop 0
	v_mul_f32_e32 v144, v96, v144
	v_mul_f32_e32 v145, v97, v145
	v_mul_f32_e32 v146, v98, v146
	v_mul_f32_e32 v147, v99, v147
	v_mul_f32_e32 v144, v112, v144
	v_mul_f32_e32 v145, v113, v145
	v_mul_f32_e32 v146, v114, v146
	v_mul_f32_e32 v147, v115, v147
	v_cvt_pk_bf16_f32 v152, v144, v145
	v_cvt_pk_bf16_f32 v153, v146, v147
	global_store_short v148, v152, s[82:83]
	global_store_short_d16_hi v149, v152, s[82:83]
	global_store_short v150, v153, s[82:83]
	global_store_short_d16_hi v151, v153, s[82:83]
	v_mul_f32_e32 v144, 0xbfb8aa3b, v100
	v_mul_f32_e32 v145, 0xbfb8aa3b, v101
	v_mul_f32_e32 v146, 0xbfb8aa3b, v102
	v_mul_f32_e32 v147, 0xbfb8aa3b, v103
	v_exp_f32_e32 v144, v144
	v_exp_f32_e32 v145, v145
	v_exp_f32_e32 v146, v146
	v_exp_f32_e32 v147, v147
	v_add_u32_e32 v148, 0x8f000, v229
	v_add_u32_e32 v149, 0x90600, v229
	v_add_u32_e32 v150, 0x91c00, v229
	v_add_u32_e32 v151, 0x93200, v229
	v_add_f32_e32 v144, 1.0, v144
	v_add_f32_e32 v145, 1.0, v145
	v_add_f32_e32 v146, 1.0, v146
	v_add_f32_e32 v147, 1.0, v147
	v_rcp_f32_e32 v144, v144
	v_rcp_f32_e32 v145, v145
; DI bf16_t f2bf(float x) { return (bf16_t)(pack2(x, x) & 0xffffu); }
; DI int crow(int reg, int h) { return (reg & 3) + 8 * (reg >> 2) + 4 * h; }
; DI float silu_f(float x) { return x * __builtin_amdgcn_rcpf(1.0f + __expf(-x)); }
; template <int EPI>
; DI void epilogue(const Params& p, int layer, f32x16 (&acc)[2][2], int mrow0, int ncol0, int lane) {
;     ...
;   } else if (EPI == EPI_SWIGLU) {
;     bf16_t* G = (bf16_t*)(p.ws + OFF_U);
;     const int j = (ncol0 >> 7) * 64 + ((ncol0 >> 6) & 1) * 32 + c;
; #pragma unroll
;     for (int mi = 0; mi < 2; ++mi)
; #pragma unroll
;       for (int r = 0; r < 16; ++r) {
;         int row = mrow0 + mi * 32 + crow(r, h);
;         float a1 = acc[mi][0][r], a3 = acc[mi][1][r];
;         G[(size_t)row * FFH + j] = f2bf(silu_f(a1) * a3);
;       }
; template <int EPI>
; DI void gemm_phase(const Params& p, int layer, const bf16_t* __restrict__ A, int lda, const bf16_t* __restrict__ Bt, int ldb, int K, int MT, int NT,
;                    char* smem, bool rev = false) {
;     ...
;     const int tn = t + gridDim.x;
;     const bool has_next = tn < total;
;     const int m0c = m0, n0c = n0;
;     constexpr bool PRE = (EPI != EPI_QUP && EPI != EPI_RES1 && EPI != EPI_RES2);
;     if (has_next) {
;       tile_map(tn, MT, NT, mt, nt);
;       m0 = mt * 128; n0 = nt * 128;
;       Agl = A + (size_t)(m0 + lr) * lda + lc;
;       Bgl = Bt + (size_t)(n0 + lr) * ldb + lc;
;       if (PRE) { G_LOAD(p, 0) G_LOAD(q, 64) }
;     }
;     epilogue<EPI>(p, layer, acc, m0c + wr * 64, n0c + wc * 64, lane);
;     if (!has_next) break;
;     if (!PRE) { G_LOAD(p, 0) G_LOAD(q, 64) }
;     t = tn;
	v_rcp_f32_e32 v146, v146
	v_rcp_f32_e32 v147, v147
	s_nop 0
	v_mul_f32_e32 v144, v100, v144
	v_mul_f32_e32 v145, v101, v145
	v_mul_f32_e32 v146, v102, v146
	v_mul_f32_e32 v147, v103, v147
	v_mul_f32_e32 v144, v116, v144
	v_mul_f32_e32 v145, v117, v145
	v_mul_f32_e32 v146, v118, v146
	v_mul_f32_e32 v147, v119, v147
	v_cvt_pk_bf16_f32 v154, v144, v145
	v_cvt_pk_bf16_f32 v155, v146, v147
	global_store_short v148, v154, s[82:83]
	global_store_short_d16_hi v149, v154, s[82:83]
	global_store_short v150, v155, s[82:83]
	global_store_short_d16_hi v151, v155, s[82:83]
	v_mul_f32_e32 v144, 0xbfb8aa3b, v104
	v_mul_f32_e32 v145, 0xbfb8aa3b, v105
	v_mul_f32_e32 v146, 0xbfb8aa3b, v106
	v_mul_f32_e32 v147, 0xbfb8aa3b, v107
	v_exp_f32_e32 v144, v144
	v_exp_f32_e32 v145, v145
	v_exp_f32_e32 v146, v146
	v_exp_f32_e32 v147, v147
	v_add_u32_e32 v148, 0x9a000, v229
	v_add_u32_e32 v149, 0x9b600, v229
	v_add_u32_e32 v150, 0x9cc00, v229
	v_add_u32_e32 v151, 0x9e200, v229
	v_add_f32_e32 v144, 1.0, v144
	v_add_f32_e32 v145, 1.0, v145
	v_add_f32_e32 v146, 1.0, v146
	v_add_f32_e32 v147, 1.0, v147
	v_rcp_f32_e32 v144, v144
	v_rcp_f32_e32 v145, v145
	v_rcp_f32_e32 v146, v146
	v_rcp_f32_e32 v147, v147
	s_nop 0
	v_mul_f32_e32 v144, v104, v144
	v_mul_f32_e32 v145, v105, v145
	v_mul_f32_e32 v146, v106, v146
	v_mul_f32_e32 v147, v107, v147
	v_mul_f32_e32 v144, v120, v144
	v_mul_f32_e32 v145, v121, v145
	v_mul_f32_e32 v146, v122, v146
	v_mul_f32_e32 v147, v123, v147
	v_cvt_pk_bf16_f32 v152, v144, v145
	v_cvt_pk_bf16_f32 v153, v146, v147
	global_store_short v148, v152, s[82:83]
	global_store_short_d16_hi v149, v152, s[82:83]
	global_store_short v150, v153, s[82:83]
	global_store_short_d16_hi v151, v153, s[82:83]
	v_mul_f32_e32 v144, 0xbfb8aa3b, v108
	v_mul_f32_e32 v145, 0xbfb8aa3b, v109
	v_mul_f32_e32 v146, 0xbfb8aa3b, v110
	v_mul_f32_e32 v147, 0xbfb8aa3b, v111
	v_exp_f32_e32 v144, v144
	v_exp_f32_e32 v145, v145
	v_exp_f32_e32 v146, v146
	v_exp_f32_e32 v147, v147
	v_add_u32_e32 v148, 0xa5000, v229
	v_add_u32_e32 v149, 0xa6600, v229
	v_add_u32_e32 v150, 0xa7c00, v229
	v_add_u32_e32 v151, 0xa9200, v229
	v_add_f32_e32 v144, 1.0, v144
	v_add_f32_e32 v145, 1.0, v145
	v_add_f32_e32 v146, 1.0, v146
	v_add_f32_e32 v147, 1.0, v147
	v_rcp_f32_e32 v144, v144
	v_rcp_f32_e32 v145, v145
	v_rcp_f32_e32 v146, v146
	v_rcp_f32_e32 v147, v147
	s_nop 0
	v_mul_f32_e32 v144, v108, v144
	v_mul_f32_e32 v145, v109, v145
	v_mul_f32_e32 v146, v110, v146
	v_mul_f32_e32 v147, v111, v147
	v_mul_f32_e32 v144, v124, v144
	v_mul_f32_e32 v145, v125, v145
	v_mul_f32_e32 v146, v126, v146
	v_mul_f32_e32 v147, v127, v147
	v_cvt_pk_bf16_f32 v154, v144, v145
	v_cvt_pk_bf16_f32 v155, v146, v147
	global_store_short v148, v154, s[82:83]
	global_store_short_d16_hi v149, v154, s[82:83]
	global_store_short v150, v155, s[82:83]
	global_store_short_d16_hi v151, v155, s[82:83]
	s_branch .Lmg_next
.Lmg_next:
	s_add_u32 s66, s66, s65
	s_branch .Lmg_tile
.Lmg_done:
	s_mov_b32 s100, s52
	v_readlane_b32 s52, v254, 0
	v_readlane_b32 s53, v254, 1
	v_readlane_b32 s54, v254, 2
	v_readlane_b32 s55, v254, 3
	v_readlane_b32 s56, v254, 4
	v_readlane_b32 s57, v254, 5
	v_readlane_b32 s58, v254, 6
	v_readlane_b32 s59, v254, 7
	v_readlane_b32 s60, v254, 8
	v_readlane_b32 s61, v254, 9
	v_readlane_b32 s62, v254, 10
	v_readlane_b32 s63, v254, 11
	v_readlane_b32 s64, v254, 12
	v_readlane_b32 s65, v254, 13
	v_readlane_b32 s66, v254, 14
	v_readlane_b32 s67, v254, 15
	v_readlane_b32 s68, v254, 16
	v_readlane_b32 s69, v254, 17
	v_readlane_b32 s70, v254, 18
	v_readlane_b32 s71, v254, 19
	v_readlane_b32 s72, v254, 20
	v_readlane_b32 s73, v254, 21
	v_readlane_b32 s74, v254, 22
	v_readlane_b32 s75, v254, 23
	v_readlane_b32 s76, v254, 24
	v_readlane_b32 s77, v254, 25
	v_readlane_b32 s78, v254, 26
	v_readlane_b32 s79, v254, 27
	v_readlane_b32 s80, v254, 28
	v_readlane_b32 s81, v254, 29
	v_readlane_b32 s82, v254, 30
	v_readlane_b32 s83, v254, 31
	v_readlane_b32 s84, v254, 32
	v_readlane_b32 s85, v254, 33
	v_readlane_b32 s86, v254, 34
	v_readlane_b32 s87, v254, 35
	v_readlane_b32 s88, v254, 36
	v_readlane_b32 s89, v254, 37
	v_readlane_b32 s90, v254, 38
	v_readlane_b32 s91, v254, 39
	s_nop 3
	s_cmp_eq_u32 s100, 1
	s_cbranch_scc1 .LBB0_1546
	s_cmp_eq_u32 s100, 2
	s_cbranch_scc1 .LBB0_1650
	s_cmp_eq_u32 s100, 3
	s_cbranch_scc1 .LBB0_1711
	s_branch .LBB0_458

; __global__ void __launch_bounds__(THREADS, 2) fwd_megakernel(Params p) {
;   __shared__ __attribute__((aligned(16))) char smem[79872];
	.amdhsa_kernel _Z14fwd_megakernel6Params
		.amdhsa_group_segment_fixed_size 79872
		.amdhsa_private_segment_fixed_size 0
		.amdhsa_kernarg_size 504
		.amdhsa_user_sgpr_count 2
		.amdhsa_user_sgpr_dispatch_ptr 0
		.amdhsa_user_sgpr_queue_ptr 0
		.amdhsa_user_sgpr_kernarg_segment_ptr 1
		.amdhsa_user_sgpr_dispatch_id 0
		.amdhsa_user_sgpr_kernarg_preload_length 0
		.amdhsa_user_sgpr_kernarg_preload_offset 0
		.amdhsa_user_sgpr_private_segment_size 0
		.amdhsa_uses_dynamic_stack 0
		.amdhsa_enable_private_segment 0
		.amdhsa_system_sgpr_workgroup_id_x 1
		.amdhsa_system_sgpr_workgroup_id_y 0
		.amdhsa_system_sgpr_workgroup_id_z 0
		.amdhsa_system_sgpr_workgroup_info 0
		.amdhsa_system_vgpr_workitem_id 2
		.amdhsa_next_free_vgpr 256
		.amdhsa_next_free_sgpr 102
		.amdhsa_accum_offset 256
		.amdhsa_reserve_vcc 1
		.amdhsa_float_round_mode_32 0
		.amdhsa_float_round_mode_16_64 0
		.amdhsa_float_denorm_mode_32 3
		.amdhsa_float_denorm_mode_16_64 3
		.amdhsa_dx10_clamp 1
		.amdhsa_ieee_mode 1
		.amdhsa_fp16_overflow 0
		.amdhsa_tg_split 0
		.amdhsa_exception_fp_ieee_invalid_op 0
		.amdhsa_exception_fp_denorm_src 0
		.amdhsa_exception_fp_ieee_div_zero 0
		.amdhsa_exception_fp_ieee_overflow 0
		.amdhsa_exception_fp_ieee_underflow 0
		.amdhsa_exception_fp_ieee_inexact 0
		.amdhsa_exception_int_div_zero 0
	.end_amdhsa_kernel

; __global__ void __launch_bounds__(THREADS, 2) fwd_megakernel(Params p) {
;   __shared__ __attribute__((aligned(16))) char smem[79872];
amdhsa.kernels:
  - .agpr_count:     0
    .args:
      - .offset:         0
        .size:           248
        .value_kind:     by_value
      - .offset:         248
        .size:           4
        .value_kind:     hidden_block_count_x
      - .offset:         252
        .size:           4
        .value_kind:     hidden_block_count_y
      - .offset:         256
        .size:           4
        .value_kind:     hidden_block_count_z
      - .offset:         260
        .size:           2
        .value_kind:     hidden_group_size_x
      - .offset:         262
        .size:           2
        .value_kind:     hidden_group_size_y
      - .offset:         264
        .size:           2
        .value_kind:     hidden_group_size_z
      - .offset:         266
        .size:           2
        .value_kind:     hidden_remainder_x
      - .offset:         268
        .size:           2
        .value_kind:     hidden_remainder_y
      - .offset:         270
        .size:           2
        .value_kind:     hidden_remainder_z
      - .offset:         288
        .size:           8
        .value_kind:     hidden_global_offset_x
      - .offset:         296
        .size:           8
        .value_kind:     hidden_global_offset_y
      - .offset:         304
        .size:           8
        .value_kind:     hidden_global_offset_z
      - .offset:         312
        .size:           2
        .value_kind:     hidden_grid_dims
      - .offset:         336
        .size:           8
        .value_kind:     hidden_multigrid_sync_arg
    .group_segment_fixed_size: 79872
    .kernarg_segment_align: 8
    .kernarg_segment_size: 504
    .language:       OpenCL C
    .language_version:
      - 2
      - 0
    .max_flat_workgroup_size: 256
    .name:           _Z14fwd_megakernel6Params
    .private_segment_fixed_size: 0
    .sgpr_count:     108
    .sgpr_spill_count: 190
    .symbol:         _Z14fwd_megakernel6Params.kd
    .uniform_work_group_size: 1
    .uses_dynamic_stack: false
    .vgpr_count:     256
    .vgpr_spill_count: 0
    .wavefront_size: 64
